# adds: V tile loads of the three prep kinds issued before the in-place q/k stores (no store-ack drain at their wait)
# baseline (speedup 1.0000x reference)
;   __device__ __forceinline__ bf16* h() const { unsigned o_ = (unsigned)(OFF_h); asm volatile("" : "+s"(o_)); return (bf16*)(ws + o_); }
;   __device__ __forceinline__ bf16* U() const { unsigned o_ = (unsigned)(OFF_U); asm volatile("" : "+s"(o_)); return (bf16*)(ws + o_); }
;   __device__ __forceinline__ bf16* y() const { unsigned o_ = (unsigned)(OFF_y); asm volatile("" : "+s"(o_)); return (bf16*)(ws + o_); }
; __device__ __forceinline__ void load_vxT(const bf16* vsrc, bf16* VxT, int c, int rbase, int rpad) {
;   const int tid = otid(), e0 = (tid >> 7) * 16, t = tid & 127;
;   const bf16* vs = vsrc + TROW(t) * US + e0;
;   const uint4 v0 = *(const uint4*)vs, v1 = *(const uint4*)(vs + 8);
; __device__ void ret_prep_unit(const P& p, int layer, int unit, char* smem) {
;   const int tid = otid();
;   const int c = unit % NCH, bh = unit / NCH, h = bh & 3, b = bh >> 2;
;   bf16* KxT = (bf16*)smem;
;   bf16* VxT = KxT + 64 * 136;
;   const int rbase = b * RB + c * 128 - PADB, rpad = RREAL + b * PADB;
;   const float l2g = __log2f(1.f - exp2f(-5.f - (float)h));
;   __syncthreads();
;   {
;     const int t = tid >> 2, i0 = (tid & 3) * 8;
;     const int sidx = c * 128 + t;
;     const float4 ca = *(const float4*)(p.rope_cos() + sidx * 32 + i0), cb = *(const float4*)(p.rope_cos() + sidx * 32 + i0 + 4);
;     const float4 sa = *(const float4*)(p.rope_sin() + sidx * 32 + i0), sb = *(const float4*)(p.rope_sin() + sidx * 32 + i0 + 4);
;     const float cs[8] = {ca.x, ca.y, ca.z, ca.w, cb.x, cb.y, cb.z, cb.w};
;     const float sn[8] = {sa.x, sa.y, sa.z, sa.w, sb.x, sb.y, sb.z, sb.w};
;     bf16* qp = p.U() + TROW(t) * US + C_RQ + h * 64 + i0;
;     bf16* kp = p.U() + TROW(t) * US + C_RK + h * 64 + i0;
;     const uint4 q1 = *(const uint4*)qp, q2 = *(const uint4*)(qp + 32), k1 = *(const uint4*)kp, k2 = *(const uint4*)(kp + 32);
;     float a[8], bb[8], o1[8], o2[8];
;     UNPK8(q1, a); UNPK8(q2, bb);
; #pragma unroll
;     for (int i = 0; i < 8; ++i) { o1[i] = a[i] * cs[i] - bb[i] * sn[i]; o2[i] = a[i] * sn[i] + bb[i] * cs[i]; }
;     uint4 o;
;     o.x = pk2(o1[0], o1[1]); o.y = pk2(o1[2], o1[3]); o.z = pk2(o1[4], o1[5]); o.w = pk2(o1[6], o1[7]);
;     *(uint4*)qp = o;
;     o.x = pk2(o2[0], o2[1]); o.y = pk2(o2[2], o2[3]); o.z = pk2(o2[4], o2[5]); o.w = pk2(o2[6], o2[7]);
;     *(uint4*)(qp + 32) = o;
.LBB0_209:
	s_add_i32 s0, s68, 0xfffffe18
	s_mul_i32 s1, s0, 0xfc1
	s_lshr_b32 s1, s1, 21
	s_mulk_i32 s1, 0x208
	s_sub_i32 s1, s0, s1
	s_and_b32 s33, s1, 0xffff
	s_cmpk_gt_u32 s0, 0x207
	s_mov_b64 s[0:1], -1
	s_cbranch_scc0 .LBB0_249
	s_and_b32 s1, s33, 0xffff
	s_mulk_i32 s1, 0xfc1
	s_lshr_b32 s2, s1, 18
	s_mulk_i32 s2, 0x41
	s_sub_i32 s15, s33, s2
	s_bfe_u32 s14, s1, 0x20012
	s_lshr_b32 s6, s1, 20
	s_lshl_b32 s1, s15, 7
	s_add_i32 s0, s68, 0xfffffc10
	s_and_b32 s4, s1, 0xff80
	s_cmpk_gt_u32 s0, 0x207
	s_mul_i32 s5, s6, 0x2010
	s_mov_b64 s[0:1], -1
	s_mulk_i32 s6, 0x70
	s_cbranch_scc0 .LBB0_216
	v_cvt_f32_ubyte0_e32 v1, s14
	s_add_i32 s0, s4, s5
	v_sub_f32_e32 v40, 0xc0a00000, v1
	s_mov_b32 s13, 0xc2fc0000
	v_mov_b32_e32 v0, v136
	s_add_i32 s7, s0, 0xffffff90
	s_add_i32 s8, s6, 0x4020
	v_cmp_gt_f32_e32 vcc, s13, v40
	s_and_b64 s[0:1], vcc, exec
	v_ashrrev_i32_e32 v42, 2, v0
	v_lshlrev_b32_e32 v0, 3, v0
	s_mov_b32 s0, 0x1c008700
	s_barrier
	v_and_b32_e32 v43, 24, v0
	v_add_lshl_u32 v0, v42, s4, 5
	s_cselect_b32 s9, 0xffffffc0, 0
	s_add_u32 s0, s76, s0
	v_ashrrev_i32_e32 v1, 31, v0
	s_addc_u32 s1, s77, 0
	v_lshlrev_b64 v[4:5], 2, v[0:1]
	v_lshl_add_u64 v[0:1], s[0:1], 0, v[4:5]
	v_lshlrev_b32_e32 v138, 2, v43
	v_lshl_add_u64 v[0:1], v[0:1], 0, v[138:139]
	s_mov_b32 s0, 0x1c008700
	global_load_dwordx4 v[8:11], v[0:1], off
	s_add_u32 s0, s76, s0
	s_addc_u32 s1, s77, 0
	v_lshl_add_u64 v[0:1], s[0:1], 0, v[4:5]
	v_lshl_add_u64 v[0:1], v[0:1], 0, v[138:139]
	s_mov_b32 s0, 0x1c10c700
	global_load_dwordx4 v[0:3], v[0:1], off offset:16
	s_add_u32 s0, s76, s0
	s_addc_u32 s1, s77, 0
	v_lshl_add_u64 v[6:7], s[0:1], 0, v[4:5]
	v_lshl_add_u64 v[6:7], v[6:7], 0, v[138:139]
	s_mov_b32 s0, 0x1c10c700
	global_load_dwordx4 v[12:15], v[6:7], off
	s_add_u32 s0, s76, s0
	s_addc_u32 s1, s77, 0
	v_lshl_add_u64 v[4:5], s[0:1], 0, v[4:5]
	v_lshl_add_u64 v[4:5], v[4:5], 0, v[138:139]
	s_mov_b32 s0, 0x6180000
	global_load_dwordx4 v[16:19], v[4:5], off offset:16
	s_add_u32 s2, s76, s0
	s_addc_u32 s3, s77, 0
	s_and_b32 s0, 0xffff, s15
	s_cmp_eq_u32 s0, 0
	s_movk_i32 s12, 0x70
	v_cndmask_b32_e32 v41, 0, v194, vcc
	s_cselect_b64 s[0:1], -1, 0
	v_cmp_gt_i32_e32 vcc, s12, v42
	v_mov_b32_e32 v44, s7
	v_mov_b32_e32 v45, s8
	s_and_b64 vcc, s[0:1], vcc
	v_cndmask_b32_e32 v4, v44, v45, vcc
	v_add_u32_e32 v6, v4, v42
	v_mov_b64_e32 v[4:5], s[2:3]
	v_mad_i64_i32 v[4:5], s[2:3], v6, s54, v[4:5]
	s_lshl_b32 s96, s14, 7
	v_lshl_add_u64 v[4:5], v[4:5], 0, s[96:97]
	v_lshlrev_b32_e32 v138, 1, v43
	v_lshl_add_u64 v[4:5], v[4:5], 0, v[138:139]
	s_movk_i32 s7, 0x1000
	v_add_co_u32_e32 v36, vcc, s7, v4
	s_mov_b64 s[16:17], 0x1430
	s_mov_b32 s2, 0x6180000
	v_addc_co_u32_e32 v37, vcc, 0, v5, vcc
	v_lshl_add_u64 v[38:39], v[4:5], 0, s[16:17]
	global_load_dwordx4 v[20:23], v[36:37], off offset:1072
	global_load_dwordx4 v[24:27], v[38:39], off offset:64
	s_add_u32 s2, s76, s2
	s_addc_u32 s3, s77, 0
	v_mov_b64_e32 v[4:5], s[2:3]
	v_mad_i64_i32 v[4:5], s[2:3], v6, s54, v[4:5]
	v_lshl_add_u64 v[4:5], v[4:5], 0, s[96:97]
	v_lshl_add_u64 v[4:5], v[4:5], 0, v[138:139]
	v_add_co_u32_e32 v6, vcc, s7, v4
	s_mov_b64 s[2:3], 0x1630
	s_nop 0
	v_addc_co_u32_e32 v7, vcc, 0, v5, vcc
	v_lshl_add_u64 v[4:5], v[4:5], 0, s[2:3]
	global_load_dwordx4 v[28:31], v[6:7], off offset:1584
	global_load_dwordx4 v[32:35], v[4:5], off offset:64
	s_add_u32 s18, s76, 0x6180000
	s_addc_u32 s19, s77, 0
	s_add_u32 s18, s18, s96
	s_addc_u32 s19, s19, 0
	s_add_u32 s18, s18, 0x1830
	s_addc_u32 s19, s19, 0
	v_and_b32_e32 v230, 0x7f, v136
	v_cmp_gt_u32_e32 vcc, s12, v230
	s_and_b64 vcc, s[0:1], vcc
	v_cndmask_b32_e32 v224, v44, v45, vcc
	v_ashrrev_i32_e32 v231, 3, v136
	v_add_u32_e32 v224, v224, v230
	v_and_b32_e32 v228, -16, v231
	v_mov_b32_e32 v222, s18
	v_mov_b32_e32 v223, s19
	v_mad_i64_i32 v[222:223], s[22:23], v224, s54, v[222:223]
	v_ashrrev_i32_e32 v229, 31, v228
	v_lshl_add_u64 v[226:227], v[228:229], 1, v[222:223]
	global_load_dwordx4 v[232:235], v[226:227], off
	global_load_dwordx4 v[236:239], v[226:227], off offset:16
	v_add_f32_e32 v40, v40, v41
	v_exp_f32_e32 v40, v40
	s_mov_b32 s2, 0x6180000
	s_movk_i32 s10, 0x1000
	s_movk_i32 s44, 0x70
	v_ldexp_f32 v40, v40, s9
	v_sub_f32_e32 v40, 1.0, v40
	v_log_f32_e32 v40, v40
	s_waitcnt vmcnt(5)
	v_lshlrev_b32_e32 v41, 16, v20
	s_waitcnt vmcnt(4)
	v_lshlrev_b32_e32 v49, 16, v24
	v_and_b32_e32 v24, 0xffff0000, v24
	v_and_b32_e32 v20, 0xffff0000, v20
	v_lshlrev_b32_e32 v50, 16, v25
	v_mul_f32_e32 v53, v12, v49
	v_mul_f32_e32 v49, v8, v49
	v_mul_f32_e32 v54, v13, v24
	v_mul_f32_e32 v24, v9, v24
	v_lshlrev_b32_e32 v46, 16, v21
	v_and_b32_e32 v25, 0xffff0000, v25
	v_fma_f32 v53, v8, v41, -v53
	v_fmac_f32_e32 v49, v12, v41
	v_fma_f32 v41, v9, v20, -v54
	v_fmac_f32_e32 v24, v13, v20
	v_mul_f32_e32 v20, v14, v50
	v_and_b32_e32 v21, 0xffff0000, v21
	v_lshlrev_b32_e32 v51, 16, v26
	v_fma_f32 v54, v10, v46, -v20
	v_mul_f32_e32 v50, v10, v50
	v_mul_f32_e32 v20, v15, v25
	v_lshlrev_b32_e32 v47, 16, v22
	v_and_b32_e32 v26, 0xffff0000, v26
	v_fmac_f32_e32 v50, v14, v46
	v_fma_f32 v46, v11, v21, -v20
	v_mul_f32_e32 v20, v16, v51
	v_and_b32_e32 v22, 0xffff0000, v22
	v_lshlrev_b32_e32 v52, 16, v27
	v_fma_f32 v55, v0, v47, -v20
	v_mul_f32_e32 v51, v0, v51
	v_mul_f32_e32 v20, v17, v26
	v_lshlrev_b32_e32 v48, 16, v23
	v_and_b32_e32 v27, 0xffff0000, v27
	v_fmac_f32_e32 v51, v16, v47
	v_fma_f32 v47, v1, v22, -v20
	v_mul_f32_e32 v20, v18, v52
	v_and_b32_e32 v23, 0xffff0000, v23
	v_mul_f32_e32 v25, v11, v25
	v_fma_f32 v56, v2, v48, -v20
	v_mul_f32_e32 v52, v2, v52
	v_mul_f32_e32 v20, v19, v27
	v_fmac_f32_e32 v25, v15, v21
	v_mul_f32_e32 v26, v1, v26
	v_fmac_f32_e32 v52, v18, v48
	v_fma_f32 v48, v3, v23, -v20
	v_mul_f32_e32 v27, v3, v27
	v_cvt_pk_bf16_f32 v20, v53, v41
	v_cvt_pk_bf16_f32 v21, v54, v46
	v_fmac_f32_e32 v26, v17, v22
	v_fmac_f32_e32 v27, v19, v23
	v_cvt_pk_bf16_f32 v22, v55, v47
	v_cvt_pk_bf16_f32 v23, v56, v48
	global_store_dwordx4 v[36:37], v[20:23], off offset:1072
	s_waitcnt vmcnt(3)
;   __device__ __forceinline__ bf16* h() const { unsigned o_ = (unsigned)(OFF_h); asm volatile("" : "+s"(o_)); return (bf16*)(ws + o_); }
;   __device__ __forceinline__ bf16* U() const { unsigned o_ = (unsigned)(OFF_U); asm volatile("" : "+s"(o_)); return (bf16*)(ws + o_); }
;   __device__ __forceinline__ bf16* y() const { unsigned o_ = (unsigned)(OFF_y); asm volatile("" : "+s"(o_)); return (bf16*)(ws + o_); }
; __device__ __forceinline__ void load_vxT(const bf16* vsrc, bf16* VxT, int c, int rbase, int rpad) {
;   const int tid = otid(), e0 = (tid >> 7) * 16, t = tid & 127;
;   const bf16* vs = vsrc + TROW(t) * US + e0;
;   const uint4 v0 = *(const uint4*)vs, v1 = *(const uint4*)(vs + 8);
;   VxT[(e0 + 0) * 136 + t] = (bf16)(v0.x & 0xffffu); VxT[(e0 + 1) * 136 + t] = (bf16)(v0.x >> 16);
;   VxT[(e0 + 2) * 136 + t] = (bf16)(v0.y & 0xffffu); VxT[(e0 + 3) * 136 + t] = (bf16)(v0.y >> 16);
;   VxT[(e0 + 4) * 136 + t] = (bf16)(v0.z & 0xffffu); VxT[(e0 + 5) * 136 + t] = (bf16)(v0.z >> 16);
;   VxT[(e0 + 6) * 136 + t] = (bf16)(v0.w & 0xffffu); VxT[(e0 + 7) * 136 + t] = (bf16)(v0.w >> 16);
;   VxT[(e0 + 8) * 136 + t] = (bf16)(v1.x & 0xffffu); VxT[(e0 + 9) * 136 + t] = (bf16)(v1.x >> 16);
;   VxT[(e0 + 10) * 136 + t] = (bf16)(v1.y & 0xffffu); VxT[(e0 + 11) * 136 + t] = (bf16)(v1.y >> 16);
;   VxT[(e0 + 12) * 136 + t] = (bf16)(v1.z & 0xffffu); VxT[(e0 + 13) * 136 + t] = (bf16)(v1.z >> 16);
;   VxT[(e0 + 14) * 136 + t] = (bf16)(v1.w & 0xffffu); VxT[(e0 + 15) * 136 + t] = (bf16)(v1.w >> 16);
; }
; __device__ void ret_prep_unit(const P& p, int layer, int unit, char* smem) {
;     ...
;     UNPK8(k1, a); UNPK8(k2, bb);
;     const float kdec = exp2f((float)(127 - t) * l2g);
; #pragma unroll
;     for (int i = 0; i < 8; ++i) {
;       o1[i] = (a[i] * cs[i] - bb[i] * sn[i]) * 0.125f; o2[i] = (a[i] * sn[i] + bb[i] * cs[i]) * 0.125f;
;     }
; #pragma unroll
;     for (int i = 0; i < 8; ++i) { KxT[(i0 + i) * 136 + t] = f2bf(o1[i] * kdec); KxT[(32 + i0 + i) * 136 + t] = f2bf(o2[i] * kdec); }
;     o.x = pk2(o1[0], o1[1]); o.y = pk2(o1[2], o1[3]); o.z = pk2(o1[4], o1[5]); o.w = pk2(o1[6], o1[7]);
;     *(uint4*)kp = o;
;     o.x = pk2(o2[0], o2[1]); o.y = pk2(o2[2], o2[3]); o.z = pk2(o2[4], o2[5]); o.w = pk2(o2[6], o2[7]);
;     *(uint4*)(kp + 32) = o;
;     load_vxT(p.U() + C_RV + h * 64, VxT, c, rbase, rpad);
	v_lshlrev_b32_e32 v36, 16, v35
	v_and_b32_e32 v35, 0xffff0000, v35
	v_cvt_pk_bf16_f32 v20, v49, v24
	v_cvt_pk_bf16_f32 v21, v50, v25
	v_cvt_pk_bf16_f32 v22, v51, v26
	v_cvt_pk_bf16_f32 v23, v52, v27
	global_store_dwordx4 v[38:39], v[20:23], off offset:64
	v_lshlrev_b32_e32 v24, 16, v30
	v_and_b32_e32 v25, 0xffff0000, v30
	v_lshlrev_b32_e32 v20, 16, v28
	v_and_b32_e32 v21, 0xffff0000, v28
	v_lshlrev_b32_e32 v28, 16, v32
	v_mul_f32_e32 v38, v12, v28
	v_lshlrev_b32_e32 v22, 16, v29
	v_and_b32_e32 v23, 0xffff0000, v29
	v_and_b32_e32 v29, 0xffff0000, v32
	v_fma_f32 v38, v8, v20, -v38
	v_mul_f32_e32 v8, v8, v28
	v_fmac_f32_e32 v8, v12, v20
	v_mul_f32_e32 v12, v13, v29
	v_lshlrev_b32_e32 v30, 16, v33
	v_fma_f32 v12, v9, v21, -v12
	v_mul_f32_e32 v9, v9, v29
	v_fmac_f32_e32 v9, v13, v21
	v_mul_f32_e32 v13, v14, v30
	v_lshlrev_b32_e32 v26, 16, v31
	v_and_b32_e32 v27, 0xffff0000, v31
	v_and_b32_e32 v31, 0xffff0000, v33
	v_fma_f32 v13, v10, v22, -v13
	v_mul_f32_e32 v10, v10, v30
	v_fmac_f32_e32 v10, v14, v22
	v_mul_f32_e32 v14, v15, v31
	v_lshlrev_b32_e32 v32, 16, v34
	v_fma_f32 v14, v11, v23, -v14
	v_mul_f32_e32 v11, v11, v31
	v_fmac_f32_e32 v11, v15, v23
	v_mul_f32_e32 v15, v16, v32
	v_fma_f32 v15, v0, v24, -v15
	v_mul_f32_e32 v0, v0, v32
	v_and_b32_e32 v34, 0xffff0000, v34
	v_fmac_f32_e32 v0, v16, v24
	v_sub_u32_e32 v33, 0x7f, v42
	v_mul_f32_e32 v16, 0x3e000000, v0
	v_mul_f32_e32 v0, v17, v34
	v_cvt_f32_i32_e32 v33, v33
	v_fma_f32 v0, v1, v25, -v0
	v_mul_f32_e32 v20, 0x3e000000, v0
	v_mul_f32_e32 v0, v1, v34
	v_fmac_f32_e32 v0, v17, v25
	v_mul_f32_e32 v17, 0x3e000000, v0
	v_mul_f32_e32 v0, v18, v36
	v_mul_f32_e32 v37, v40, v33
	v_fma_f32 v0, v2, v26, -v0
	v_mul_f32_e32 v21, 0x3e000000, v0
	v_mul_f32_e32 v0, v2, v36
	v_cmp_gt_f32_e32 vcc, s13, v37
	v_fmac_f32_e32 v0, v18, v26
	v_mul_f32_e32 v18, 0x3e000000, v0
	v_cndmask_b32_e32 v1, 0, v194, vcc
	v_mul_f32_e32 v0, v19, v35
	v_fmac_f32_e32 v1, v40, v33
	v_fma_f32 v0, v3, v27, -v0
	v_exp_f32_e32 v1, v1
	v_mul_f32_e32 v22, 0x3e000000, v0
	v_mul_f32_e32 v0, v3, v35
	v_fmac_f32_e32 v0, v19, v27
	v_mul_f32_e32 v19, 0x3e000000, v0
	v_cndmask_b32_e32 v0, 0, v195, vcc
	v_mul_f32_e32 v38, 0x3e000000, v38
	v_ldexp_f32 v0, v1, v0
	v_mul_u32_u24_e32 v3, 0x88, v43
	v_lshlrev_b32_e32 v1, 1, v42
	v_mul_f32_e32 v2, v0, v38
	v_lshlrev_b32_e32 v3, 1, v3
	v_mul_f32_e32 v8, 0x3e000000, v8
	v_cvt_pk_bf16_f32 v2, v2, v139
	v_add3_u32 v23, s45, v1, v3
	ds_write_b16 v23, v2
	v_mul_f32_e32 v2, v0, v8
	v_mul_f32_e32 v12, 0x3e000000, v12
	v_cvt_pk_bf16_f32 v2, v2, v139
	v_add3_u32 v1, s45, v3, v1
	ds_write_b16 v1, v2 offset:8704
	v_mul_f32_e32 v2, v0, v12
	v_mul_f32_e32 v9, 0x3e000000, v9
	v_cvt_pk_bf16_f32 v2, v2, v139
	ds_write_b16 v23, v2 offset:272
	v_mul_f32_e32 v2, v0, v9
	v_mul_f32_e32 v13, 0x3e000000, v13
	v_cvt_pk_bf16_f32 v2, v2, v139
	ds_write_b16 v1, v2 offset:8976
	v_mul_f32_e32 v2, v0, v13
	v_mul_f32_e32 v10, 0x3e000000, v10
	v_cvt_pk_bf16_f32 v2, v2, v139
	ds_write_b16 v23, v2 offset:544
	v_mul_f32_e32 v2, v0, v10
	v_mul_f32_e32 v14, 0x3e000000, v14
	v_cvt_pk_bf16_f32 v2, v2, v139
	ds_write_b16 v1, v2 offset:9248
	v_mul_f32_e32 v2, v0, v14
	v_mul_f32_e32 v11, 0x3e000000, v11
	v_cvt_pk_bf16_f32 v2, v2, v139
	ds_write_b16 v23, v2 offset:816
	v_mul_f32_e32 v2, v0, v11
	v_mul_f32_e32 v15, 0x3e000000, v15
	v_cvt_pk_bf16_f32 v2, v2, v139
	ds_write_b16 v1, v2 offset:9520
	v_mul_f32_e32 v2, v0, v15
	v_cvt_pk_bf16_f32 v2, v2, v139
	ds_write_b16 v23, v2 offset:1088
	v_mul_f32_e32 v2, v0, v16
	v_cvt_pk_bf16_f32 v2, v2, v139
	ds_write_b16 v1, v2 offset:9792
	v_mul_f32_e32 v2, v0, v20
	v_cvt_pk_bf16_f32 v2, v2, v139
	ds_write_b16 v23, v2 offset:1360
	v_mul_f32_e32 v2, v0, v17
	v_cvt_pk_bf16_f32 v2, v2, v139
	ds_write_b16 v1, v2 offset:10064
	v_mul_f32_e32 v2, v0, v21
	v_cvt_pk_bf16_f32 v2, v2, v139
	ds_write_b16 v23, v2 offset:1632
	v_mul_f32_e32 v2, v0, v18
	v_cvt_pk_bf16_f32 v2, v2, v139
	ds_write_b16 v1, v2 offset:10336
	v_mul_f32_e32 v2, v0, v22
	v_mul_f32_e32 v0, v0, v19
	v_cvt_pk_bf16_f32 v2, v2, v139
	v_cvt_pk_bf16_f32 v0, v0, v139
	ds_write_b16 v23, v2 offset:1904
	ds_write_b16 v1, v0 offset:10608
	v_cvt_pk_bf16_f32 v0, v38, v12
	v_cvt_pk_bf16_f32 v1, v13, v14
	v_cvt_pk_bf16_f32 v2, v15, v20
	v_cvt_pk_bf16_f32 v3, v21, v22
	global_store_dwordx4 v[6:7], v[0:3], off offset:1584
	s_nop 1
	v_cvt_pk_bf16_f32 v0, v8, v9
	v_cvt_pk_bf16_f32 v1, v10, v11
	v_cvt_pk_bf16_f32 v2, v16, v17
	v_cvt_pk_bf16_f32 v3, v18, v19
	global_store_dwordx4 v[4:5], v[0:3], off offset:64
	s_add_u32 s2, s76, s2
	s_addc_u32 s3, s77, 0
	s_add_u32 s2, s2, s96
	v_mov_b32_e32 v0, v136
	s_addc_u32 s3, s3, 0
	s_add_u32 s2, s2, 0x1830
	v_and_b32_e32 v10, 0x7f, v0
	v_cmp_gt_u32_e32 vcc, s12, v10
	s_addc_u32 s3, s3, 0
	s_and_b64 vcc, s[0:1], vcc
	v_cndmask_b32_e32 v1, v44, v45, vcc
	v_ashrrev_i32_e32 v11, 3, v0
	v_add_u32_e32 v2, v1, v10
	v_and_b32_e32 v8, -16, v11
	v_mov_b64_e32 v[0:1], s[2:3]
	v_mad_i64_i32 v[0:1], s[0:1], v2, s54, v[0:1]
	v_ashrrev_i32_e32 v9, 31, v8
	v_lshl_add_u64 v[4:5], v[8:9], 1, v[0:1]
	s_nop 0
	s_nop 0
	s_nop 0
	v_mul_lo_u32 v8, v8, s11
	v_lshlrev_b32_e32 v9, 1, v10
	v_add3_u32 v8, s45, v8, v9
	s_waitcnt vmcnt(5)
	ds_write_b16 v8, v232 offset:17408
	ds_write_b16_d16_hi v8, v232 offset:17680
	ds_write_b16 v8, v233 offset:17952
	ds_write_b16_d16_hi v8, v233 offset:18224
	ds_write_b16 v8, v234 offset:18496
	ds_write_b16_d16_hi v8, v234 offset:18768
	ds_write_b16 v8, v235 offset:19040
	ds_write_b16_d16_hi v8, v235 offset:19312
	s_waitcnt vmcnt(4)
	ds_write_b16 v8, v236 offset:19584
	ds_write_b16_d16_hi v8, v236 offset:19856
	ds_write_b16 v8, v237 offset:20128
	ds_write_b16_d16_hi v8, v237 offset:20400
	ds_write_b16 v8, v238 offset:20672
	ds_write_b16_d16_hi v8, v238 offset:20944
	ds_write_b16 v8, v239 offset:21216
	v_or_b32_e32 v0, 15, v11
	v_mul_lo_u32 v0, v0, s11
	v_add3_u32 v0, s45, v0, v9
	s_mov_b32 s0, 0x1b7e8700
	ds_write_b16_d16_hi v0, v239 offset:17408
	s_waitcnt lgkmcnt(0)
	s_barrier
; __device__ __forceinline__ int otid() { int t = threadIdx.x; asm volatile("" : "+v"(t)); return t; }
; #define MFMA(a, b, c) __builtin_amdgcn_mfma_f32_16x16x32_bf16((a), (b), (c), 0, 0, 0)
; template <int DK, int NE>
; __device__ __forceinline__ void local_mfma(const bf16* KxT, const bf16* VxT, float* outc, float* outn) {
;   const int tid = otid(), lane = tid & 63, w = tid >> 6, r = lane & 15, q = lane >> 4;
;   constexpr int NT_ = (DK / 16) * NE;
; #pragma unroll
;   for (int ti = 0; ti < (NT_ + 7) / 8; ++ti) {
;     const int tl = w + 8 * ti;
;     if (tl < NT_) {
;       const int dt = tl / NE, et = tl % NE;
;       f32x4 acc = f32x4{0.f, 0.f, 0.f, 0.f};
; #pragma unroll
;       for (int k0 = 0; k0 < 128; k0 += 32) {
;         const bf16x8 a = *(const bf16x8*)(KxT + (16 * dt + r) * 136 + k0 + q * 8);
;         const bf16x8 bv = *(const bf16x8*)(VxT + (16 * et + r) * 136 + k0 + q * 8);
;         acc = MFMA(a, bv, acc);
;       }
;       if (et < 4) {
; #pragma unroll
;         for (int j = 0; j < 4; ++j) outc[(16 * dt + 4 * q + j) * 64 + 16 * et + r] = acc[j];
;       } else if (r == 0) {
; #pragma unroll
;         for (int j = 0; j < 4; ++j) outn[16 * dt + 4 * q + j] = acc[j];
;       }
;     }
;   }
; }
	s_add_u32 s0, s76, s0
	s_addc_u32 s1, s77, 0
	s_lshl_b32 s2, s33, 14
	v_mov_b32_e32 v0, v136
	s_add_u32 s0, s0, s2
	s_addc_u32 s1, s1, 0
	v_ashrrev_i32_e32 v3, 6, v0
	v_bfe_u32 v1, v0, 4, 2
	v_and_b32_e32 v2, 15, v0
	v_lshl_add_u32 v0, v1, 4, v196
	v_lshlrev_b32_e32 v1, 2, v1
	v_cmp_gt_i32_e32 vcc, 16, v3
	s_and_saveexec_b64 s[2:3], vcc
	s_cbranch_execz .LBB0_213
	v_lshrrev_b32_e32 v4, 30, v3
	v_add_u32_e32 v4, v3, v4
	v_ashrrev_i32_e32 v4, 2, v4
	v_lshlrev_b32_e32 v20, 4, v4
	v_mul_i32_i24_e32 v5, 4, v4
	v_or_b32_e32 v4, v20, v2
	v_sub_u32_e32 v5, v3, v5
	v_mad_u64_u32 v[16:17], s[8:9], v4, s11, v[0:1]
	v_lshl_or_b32 v17, v5, 4, v2
	v_mad_u64_u32 v[18:19], s[8:9], v17, s11, v[0:1]
	ds_read_b128 v[4:7], v16
	ds_read_b128 v[8:11], v18 offset:17408
	s_waitcnt lgkmcnt(0)
	v_mfma_f32_16x16x32_bf16 v[4:7], v[4:7], v[8:11], 0
	ds_read_b128 v[8:11], v16 offset:64
	ds_read_b128 v[12:15], v18 offset:17472
	s_waitcnt lgkmcnt(0)
	v_mfma_f32_16x16x32_bf16 v[4:7], v[8:11], v[12:15], v[4:7]
	ds_read_b128 v[8:11], v16 offset:128
	ds_read_b128 v[12:15], v18 offset:17536
	s_waitcnt lgkmcnt(0)
	v_mfma_f32_16x16x32_bf16 v[4:7], v[8:11], v[12:15], v[4:7]
	ds_read_b128 v[8:11], v16 offset:192
	ds_read_b128 v[12:15], v18 offset:17600
	s_waitcnt lgkmcnt(0)
	v_mfma_f32_16x16x32_bf16 v[4:7], v[8:11], v[12:15], v[4:7]
	v_or_b32_e32 v8, v20, v1
	v_lshl_add_u32 v8, v8, 6, v17
	v_ashrrev_i32_e32 v9, 31, v8
	v_lshl_add_u64 v[10:11], v[8:9], 2, s[0:1]
	s_nop 3
	global_store_dword v[10:11], v4, off
	v_add_u32_e32 v10, 64, v8
	v_ashrrev_i32_e32 v11, 31, v10
	v_lshl_add_u64 v[10:11], v[10:11], 2, s[0:1]
	v_add_u32_e32 v4, 0x80, v8
	global_store_dword v[10:11], v5, off
	v_ashrrev_i32_e32 v5, 31, v4
	v_lshl_add_u64 v[4:5], v[4:5], 2, s[0:1]
	global_store_dword v[4:5], v6, off
	v_add_u32_e32 v4, 0xc0, v8
	v_ashrrev_i32_e32 v5, 31, v4
	v_lshl_add_u64 v[4:5], v[4:5], 2, s[0:1]
	global_store_dword v[4:5], v7, off

; __device__ __forceinline__ float silu(float x) { return x * sigm(x); }
; __device__ __forceinline__ int otid() { int t = threadIdx.x; asm volatile("" : "+v"(t)); return t; }
; __device__ __forceinline__ void load_vxT(const bf16* vsrc, bf16* VxT, int c, int rbase, int rpad) {
;   const int tid = otid(), e0 = (tid >> 7) * 16, t = tid & 127;
;   const bf16* vs = vsrc + TROW(t) * US + e0;
;   const uint4 v0 = *(const uint4*)vs, v1 = *(const uint4*)(vs + 8);
; __device__ void ml_prep_unit(const P& p, int layer, int unit, char* smem) {
;     ...
;     const float pet = pe[t];
; #pragma unroll
;     for (int i = 0; i < 16; ++i) {
;       aq[i] = silu(aq[i]);
;       ak[i] = silu(ak[i]) * 0.125f;
;     }
.LBB0_225:
	s_or_b64 exec, exec, s[0:1]
	s_waitcnt vmcnt(2)
	v_mul_f32_e32 v14, 0xbfb8aa3b, v74
	v_exp_f32_e32 v14, v14
	v_mul_f32_e32 v15, 0xbfb8aa3b, v84
	v_exp_f32_e32 v15, v15
	v_mul_f32_e32 v16, 0xbfb8aa3b, v85
	v_add_f32_e32 v14, 1.0, v14
	v_rcp_f32_e32 v14, v14
	v_exp_f32_e32 v16, v16
	s_waitcnt vmcnt(1)
	v_mul_f32_e32 v1, 0xbfb8aa3b, v96
	v_mul_f32_e32 v0, 0xbfb8aa3b, v90
	v_mul_f32_e32 v17, v74, v14
	v_add_f32_e32 v14, 1.0, v15
	v_mul_f32_e32 v15, 0xbfb8aa3b, v75
	v_exp_f32_e32 v15, v15
	v_rcp_f32_e32 v14, v14
	v_add_f32_e32 v16, 1.0, v16
	v_rcp_f32_e32 v16, v16
	v_add_f32_e32 v15, 1.0, v15
	v_rcp_f32_e32 v15, v15
	v_mul_f32_e32 v14, v84, v14
	v_mul_f32_e32 v20, 0x3e000000, v14
	v_mul_f32_e32 v14, v85, v16
	v_mul_f32_e32 v21, v75, v15
	v_mul_f32_e32 v15, 0xbfb8aa3b, v72
	v_mul_f32_e32 v16, 0xbfb8aa3b, v92
	v_exp_f32_e32 v15, v15
	v_exp_f32_e32 v16, v16
	v_mul_f32_e32 v22, 0x3e000000, v14
	v_exp_f32_e32 v1, v1
	v_add_f32_e32 v14, 1.0, v15
	v_add_f32_e32 v15, 1.0, v16
	v_rcp_f32_e32 v14, v14
	v_rcp_f32_e32 v15, v15
	v_mul_f32_e32 v16, 0xbfb8aa3b, v73
	v_exp_f32_e32 v16, v16
	v_mul_f32_e32 v23, v72, v14
	v_mul_f32_e32 v14, v92, v15
	v_mul_f32_e32 v24, 0x3e000000, v14
	v_add_f32_e32 v14, 1.0, v16
	v_mul_f32_e32 v15, 0xbfb8aa3b, v93
	v_rcp_f32_e32 v14, v14
	v_exp_f32_e32 v15, v15
	v_mul_f32_e32 v16, 0xbfb8aa3b, v70
	v_exp_f32_e32 v16, v16
	v_mul_f32_e32 v25, v73, v14
	v_add_f32_e32 v14, 1.0, v15
	v_rcp_f32_e32 v14, v14
	v_add_f32_e32 v15, 1.0, v16
	v_mul_f32_e32 v16, 0xbfb8aa3b, v86
	v_rcp_f32_e32 v15, v15
	v_exp_f32_e32 v16, v16
	v_mul_f32_e32 v14, v93, v14
	v_mul_f32_e32 v26, 0x3e000000, v14
	v_mul_f32_e32 v27, v70, v15
	v_add_f32_e32 v14, 1.0, v16
	v_mul_f32_e32 v15, 0xbfb8aa3b, v71
	v_mul_f32_e32 v16, 0xbfb8aa3b, v87
	v_exp_f32_e32 v15, v15
	v_exp_f32_e32 v16, v16
	v_rcp_f32_e32 v14, v14
	v_exp_f32_e32 v0, v0
	v_add_f32_e32 v15, 1.0, v15
	v_add_f32_e32 v16, 1.0, v16
	v_rcp_f32_e32 v15, v15
	v_rcp_f32_e32 v16, v16
	v_mul_f32_e32 v14, v86, v14
	v_mul_f32_e32 v28, 0x3e000000, v14
	v_mul_f32_e32 v29, v71, v15
	v_mul_f32_e32 v14, v87, v16
	v_mul_f32_e32 v15, 0xbfb8aa3b, v68
	v_mul_f32_e32 v16, 0xbfb8aa3b, v80
	v_exp_f32_e32 v15, v15
	v_exp_f32_e32 v16, v16
	v_mul_f32_e32 v30, 0x3e000000, v14
	v_add_f32_e32 v1, 1.0, v1
	v_add_f32_e32 v14, 1.0, v15
	v_add_f32_e32 v15, 1.0, v16
	v_rcp_f32_e32 v14, v14
	v_rcp_f32_e32 v15, v15
	v_mul_f32_e32 v16, 0xbfb8aa3b, v69
	v_exp_f32_e32 v16, v16
	v_mul_f32_e32 v31, v68, v14
	v_mul_f32_e32 v14, v80, v15
	v_mul_f32_e32 v32, 0x3e000000, v14
	v_add_f32_e32 v14, 1.0, v16
	v_mul_f32_e32 v15, 0xbfb8aa3b, v81
	v_rcp_f32_e32 v14, v14
	v_exp_f32_e32 v15, v15
	v_mul_f32_e32 v16, 0xbfb8aa3b, v66
	v_exp_f32_e32 v16, v16
	v_mul_f32_e32 v33, v69, v14
	v_add_f32_e32 v14, 1.0, v15
	v_rcp_f32_e32 v14, v14
	v_add_f32_e32 v15, 1.0, v16
	v_mul_f32_e32 v16, 0xbfb8aa3b, v76
	v_exp_f32_e32 v16, v16
	v_add_f32_e32 v0, 1.0, v0
	v_rcp_f32_e32 v3, v1
	v_mul_f32_e32 v1, 0xbfb8aa3b, v91
	v_rcp_f32_e32 v0, v0
	s_waitcnt vmcnt(0)
	s_and_b32 s18, 0xffff, s15
	s_cmp_eq_u32 s18, 0
	s_cselect_b64 s[18:19], -1, 0
	s_add_u32 s22, s76, 0x6180000
	s_addc_u32 s23, s77, 0
	s_lshl_b32 s24, s2, 1
	s_add_u32 s22, s22, s24
	s_addc_u32 s23, s23, 0
	s_add_u32 s22, s22, 0x1020
	s_addc_u32 s23, s23, 0
	v_and_b32_e32 v230, 0x7f, v136
	s_movk_i32 s24, 0x70
	v_cmp_gt_u32_e32 vcc, s24, v230
	s_and_b64 vcc, s[18:19], vcc
	v_mov_b32_e32 v224, s35
	v_mov_b32_e32 v225, s34
	v_cndmask_b32_e32 v224, v224, v225, vcc
	v_ashrrev_i32_e32 v231, 3, v136
	v_add_u32_e32 v224, v224, v230
	v_and_b32_e32 v228, -16, v231
	v_mov_b32_e32 v222, s22
	v_mov_b32_e32 v223, s23
	v_mad_i64_i32 v[222:223], s[24:25], v224, s54, v[222:223]
	v_ashrrev_i32_e32 v229, 31, v228
	v_lshl_add_u64 v[226:227], v[228:229], 1, v[222:223]
	global_load_dwordx4 v[232:235], v[226:227], off
	global_load_dwordx4 v[236:239], v[226:227], off offset:16
	v_exp_f32_e32 v5, v1
	v_mul_f32_e32 v11, 0xbfb8aa3b, v88
	v_mul_f32_e32 v14, v81, v14
	v_mul_f32_e32 v10, 0xbfb8aa3b, v78
	v_exp_f32_e32 v11, v11
	v_mul_f32_e32 v34, 0x3e000000, v14
	v_add_f32_e32 v14, 1.0, v16
	v_mul_f32_e32 v16, 0xbfb8aa3b, v77
	v_exp_f32_e32 v10, v10
	v_exp_f32_e32 v16, v16
	v_mul_f32_e32 v1, v90, v0
	v_mul_f32_e32 v0, v96, v3
	v_add_f32_e32 v3, 1.0, v5
	v_mul_f32_e32 v5, 0xbfb8aa3b, v97
	v_exp_f32_e32 v5, v5
	v_mul_f32_e32 v7, 0xbfb8aa3b, v94
	v_add_f32_e32 v11, 1.0, v11
	v_exp_f32_e32 v7, v7
	v_add_f32_e32 v10, 1.0, v10
	v_rcp_f32_e32 v12, v11
	v_mul_f32_e32 v11, 0xbfb8aa3b, v79
	v_rcp_f32_e32 v14, v14
	v_add_f32_e32 v16, 1.0, v16
	v_lshl_add_u32 v4, v101, 2, v196
	v_mul_f32_e32 v9, 0xbfb8aa3b, v95
	v_rcp_f32_e32 v10, v10
	v_exp_f32_e32 v13, v11
	v_rcp_f32_e32 v16, v16
	ds_read_b32 v2, v4 offset:39168
	v_add_f32_e32 v5, 1.0, v5
	v_exp_f32_e32 v9, v9
	v_rcp_f32_e32 v5, v5
	v_add_f32_e32 v7, 1.0, v7
	v_mul_f32_e32 v14, v76, v14
	v_rcp_f32_e32 v7, v7
	v_mul_f32_e32 v11, v78, v10
	v_mul_f32_e32 v10, v88, v12
	v_add_f32_e32 v12, 1.0, v13
	v_mul_f32_e32 v13, 0xbfb8aa3b, v89
	v_mul_f32_e32 v36, 0x3e000000, v14
	v_mul_f32_e32 v14, v77, v16
	v_mul_f32_e32 v0, 0x3e000000, v0
	v_add_f32_e32 v9, 1.0, v9
	v_exp_f32_e32 v13, v13
	v_mul_f32_e32 v38, 0x3e000000, v14
	v_lshlrev_b32_e32 v14, 1, v101
	v_mul_f32_e32 v5, v97, v5
	v_rcp_f32_e32 v9, v9
	v_sub_u32_e32 v4, v4, v14
	s_waitcnt lgkmcnt(0)
; __device__ __forceinline__ bf16 f2bf(float f) { return (bf16)(pk2(f, 0.f) & 0xffffu); }
; __device__ __forceinline__ void load_vxT(const bf16* vsrc, bf16* VxT, int c, int rbase, int rpad) {
;   const int tid = otid(), e0 = (tid >> 7) * 16, t = tid & 127;
;   const bf16* vs = vsrc + TROW(t) * US + e0;
;   const uint4 v0 = *(const uint4*)vs, v1 = *(const uint4*)(vs + 8);
;   VxT[(e0 + 0) * 136 + t] = (bf16)(v0.x & 0xffffu); VxT[(e0 + 1) * 136 + t] = (bf16)(v0.x >> 16);
;   VxT[(e0 + 2) * 136 + t] = (bf16)(v0.y & 0xffffu); VxT[(e0 + 3) * 136 + t] = (bf16)(v0.y >> 16);
;   VxT[(e0 + 4) * 136 + t] = (bf16)(v0.z & 0xffffu); VxT[(e0 + 5) * 136 + t] = (bf16)(v0.z >> 16);
;   VxT[(e0 + 6) * 136 + t] = (bf16)(v0.w & 0xffffu); VxT[(e0 + 7) * 136 + t] = (bf16)(v0.w >> 16);
;   VxT[(e0 + 8) * 136 + t] = (bf16)(v1.x & 0xffffu); VxT[(e0 + 9) * 136 + t] = (bf16)(v1.x >> 16);
;   VxT[(e0 + 10) * 136 + t] = (bf16)(v1.y & 0xffffu); VxT[(e0 + 11) * 136 + t] = (bf16)(v1.y >> 16);
;   VxT[(e0 + 12) * 136 + t] = (bf16)(v1.z & 0xffffu); VxT[(e0 + 13) * 136 + t] = (bf16)(v1.z >> 16);
;   VxT[(e0 + 14) * 136 + t] = (bf16)(v1.w & 0xffffu); VxT[(e0 + 15) * 136 + t] = (bf16)(v1.w >> 16);
; }
; __device__ void ml_prep_unit(const P& p, int layer, int unit, char* smem) {
;     ...
;     const float pet = pe[t];
; #pragma unroll
;     for (int i = 0; i < 16; ++i) {
;       aq[i] = silu(aq[i]);
;       ak[i] = silu(ak[i]) * 0.125f;
;     }
; #pragma unroll
;     for (int i = 0; i < 16; ++i) KxT[(d0 + i) * 136 + t] = f2bf(pet * ak[i]);
;     bf16* dq = p.mlqk() + TROW(t) * 512 + h * 128 + d0;
;     uint4 o;
;     o.x = pk2(aq[0], aq[1]); o.y = pk2(aq[2], aq[3]); o.z = pk2(aq[4], aq[5]); o.w = pk2(aq[6], aq[7]);
;     *(uint4*)dq = o;
;     o.x = pk2(aq[8], aq[9]); o.y = pk2(aq[10], aq[11]); o.z = pk2(aq[12], aq[13]); o.w = pk2(aq[14], aq[15]);
;     *(uint4*)(dq + 8) = o;
;     o.x = pk2(ak[0], ak[1]); o.y = pk2(ak[2], ak[3]); o.z = pk2(ak[4], ak[5]); o.w = pk2(ak[6], ak[7]);
;     *(uint4*)(dq + 64) = o;
;     o.x = pk2(ak[8], ak[9]); o.y = pk2(ak[10], ak[11]); o.z = pk2(ak[12], ak[13]); o.w = pk2(ak[14], ak[15]);
;     *(uint4*)(dq + 72) = o;
;     load_vxT(p.U() + C_MV + h * 64, VxT, c, rbase, rpad);
;     if (tid < 128) {
;       VxT[64 * 136 + tid] = (bf16)0x3F80;
; #pragma unroll
;       for (int i = 65; i < 80; ++i) VxT[i * 136 + tid] = 0;
;     }
	v_mul_f32_e32 v14, v2, v0
	v_mul_f32_e32 v5, 0x3e000000, v5
	v_cvt_pk_bf16_f32 v14, v14, v139
	v_mad_u32_u24 v4, v102, s11, v4
	v_mul_f32_e32 v7, v94, v7
	ds_write_b16 v4, v14
	v_mul_f32_e32 v14, v2, v5
	v_mul_f32_e32 v7, 0x3e000000, v7
	v_add_f32_e32 v13, 1.0, v13
	v_cvt_pk_bf16_f32 v14, v14, v139
	v_mul_f32_e32 v9, v95, v9
	v_rcp_f32_e32 v13, v13
	ds_write_b16 v4, v14 offset:272
	v_mul_f32_e32 v14, v2, v7
	v_mul_f32_e32 v9, 0x3e000000, v9
	v_cvt_pk_bf16_f32 v14, v14, v139
	ds_write_b16 v4, v14 offset:544
	v_mul_f32_e32 v14, v2, v9
	v_mul_f32_e32 v10, 0x3e000000, v10
	v_cvt_pk_bf16_f32 v14, v14, v139
	v_mul_f32_e32 v13, v89, v13
	ds_write_b16 v4, v14 offset:816
	v_mul_f32_e32 v14, v2, v10
	v_mul_f32_e32 v13, 0x3e000000, v13
	v_cvt_pk_bf16_f32 v14, v14, v139
	ds_write_b16 v4, v14 offset:1088
	v_mul_f32_e32 v14, v2, v13
	v_cvt_pk_bf16_f32 v14, v14, v139
	ds_write_b16 v4, v14 offset:1360
	v_mul_f32_e32 v14, v20, v2
	v_cvt_pk_bf16_f32 v14, v14, v139
	ds_write_b16 v4, v14 offset:1632
	v_mul_f32_e32 v14, v22, v2
	v_cvt_pk_bf16_f32 v14, v14, v139
	ds_write_b16 v4, v14 offset:1904
	v_mul_f32_e32 v14, v24, v2
	v_cvt_pk_bf16_f32 v14, v14, v139
	ds_write_b16 v4, v14 offset:2176
	v_mul_f32_e32 v14, v26, v2
	v_cvt_pk_bf16_f32 v14, v14, v139
	ds_write_b16 v4, v14 offset:2448
	v_mul_f32_e32 v14, v28, v2
	v_cvt_pk_bf16_f32 v14, v14, v139
	ds_write_b16 v4, v14 offset:2720
	v_mul_f32_e32 v14, v30, v2
	v_rcp_f32_e32 v15, v15
	v_cvt_pk_bf16_f32 v14, v14, v139
	ds_write_b16 v4, v14 offset:2992
	v_mul_f32_e32 v14, v32, v2
	v_cvt_pk_bf16_f32 v14, v14, v139
	ds_write_b16 v4, v14 offset:3264
	v_mul_f32_e32 v14, v34, v2
	v_mul_f32_e32 v35, v66, v15
	v_mul_f32_e32 v15, 0xbfb8aa3b, v67
	v_cvt_pk_bf16_f32 v14, v14, v139
	v_exp_f32_e32 v15, v15
	ds_write_b16 v4, v14 offset:3536
	v_mul_f32_e32 v14, v36, v2
	v_mul_f32_e32 v2, v38, v2
	s_mov_b32 s0, 0x17683000
	v_cvt_pk_bf16_f32 v14, v14, v139
	ds_write_b16 v4, v14 offset:3808
	v_cvt_pk_bf16_f32 v2, v2, v139
	ds_write_b16 v4, v2 offset:4080
	s_add_u32 s0, s76, s0
	v_mul_f32_e32 v6, 0xbfb8aa3b, v82
	v_mul_f32_e32 v8, 0xbfb8aa3b, v83
	s_addc_u32 s1, s77, 0
	s_and_b32 s3, 0xffff, s15
	v_exp_f32_e32 v6, v6
	v_exp_f32_e32 v8, v8
	v_add_f32_e32 v15, 1.0, v15
	s_cmp_eq_u32 s3, 0
	s_movk_i32 s3, 0x70
	v_rcp_f32_e32 v15, v15
	s_cselect_b64 s[4:5], -1, 0
	v_cmp_gt_i32_e32 vcc, s3, v101
	v_mov_b32_e32 v4, s35
	v_mov_b32_e32 v39, s34
	s_and_b64 vcc, s[4:5], vcc
	v_cndmask_b32_e32 v2, v4, v39, vcc
	v_rcp_f32_e32 v3, v3
	v_add_f32_e32 v6, 1.0, v6
	v_add_f32_e32 v8, 1.0, v8
	v_add_u32_e32 v14, v2, v101
	v_rcp_f32_e32 v6, v6
	v_rcp_f32_e32 v8, v8
	v_rcp_f32_e32 v12, v12
	v_mul_f32_e32 v37, v67, v15
	v_ashrrev_i32_e32 v15, 31, v14
	v_lshlrev_b64 v[14:15], 10, v[14:15]
	v_lshl_add_u64 v[14:15], s[0:1], 0, v[14:15]
	s_lshl_b32 s96, s14, 8
	v_mul_f32_e32 v3, v91, v3
	v_lshl_add_u64 v[14:15], v[14:15], 0, s[96:97]
	v_mov_b32_e32 v65, v139
	v_mul_f32_e32 v6, v82, v6
	v_mul_f32_e32 v8, v83, v8
	v_mul_f32_e32 v12, v79, v12
	v_lshl_add_u64 v[18:19], v[14:15], 0, v[64:65]
	v_cvt_pk_bf16_f32 v14, v1, v3
	v_cvt_pk_bf16_f32 v15, v6, v8
	v_cvt_pk_bf16_f32 v16, v11, v12
	v_cvt_pk_bf16_f32 v17, v17, v21
	v_cvt_pk_bf16_f32 v0, v0, v5
	v_cvt_pk_bf16_f32 v1, v7, v9
	v_cvt_pk_bf16_f32 v2, v10, v13
	v_cvt_pk_bf16_f32 v3, v20, v22
	s_mov_b32 s0, 0x6180000
	global_store_dwordx4 v[18:19], v[14:17], off
	global_store_dwordx4 v[18:19], v[0:3], off offset:128
	s_movk_i32 s44, 0x70
	v_cvt_pk_bf16_f32 v14, v23, v25
	v_cvt_pk_bf16_f32 v15, v27, v29
	v_cvt_pk_bf16_f32 v16, v31, v33
	v_cvt_pk_bf16_f32 v17, v35, v37
	global_store_dwordx4 v[18:19], v[14:17], off offset:16
	v_cvt_pk_bf16_f32 v0, v24, v26
	v_cvt_pk_bf16_f32 v1, v28, v30
	v_cvt_pk_bf16_f32 v2, v32, v34
	v_cvt_pk_bf16_f32 v3, v36, v38
	global_store_dwordx4 v[18:19], v[0:3], off offset:144
	s_add_u32 s0, s76, s0
	s_addc_u32 s1, s77, 0
	s_lshl_b32 s2, s2, 1
	s_add_u32 s0, s0, s2
	v_mov_b32_e32 v0, v136
	s_addc_u32 s1, s1, 0
	s_add_u32 s0, s0, 0x1020
	v_and_b32_e32 v10, 0x7f, v0
	v_cmp_gt_u32_e32 vcc, s3, v10
	s_addc_u32 s1, s1, 0
	s_and_b64 vcc, s[4:5], vcc
	v_cndmask_b32_e32 v1, v4, v39, vcc
	v_ashrrev_i32_e32 v11, 3, v0
	v_add_u32_e32 v2, v1, v10
	v_and_b32_e32 v8, -16, v11
	v_mov_b64_e32 v[0:1], s[0:1]
	v_mad_i64_i32 v[0:1], s[0:1], v2, s54, v[0:1]
	v_ashrrev_i32_e32 v9, 31, v8
	v_lshl_add_u64 v[4:5], v[8:9], 1, v[0:1]
	s_nop 0
	s_nop 0
	s_nop 0
	v_mul_lo_u32 v8, v8, s11
	v_lshlrev_b32_e32 v9, 1, v10
	v_add3_u32 v8, s45, v8, v9
	s_waitcnt vmcnt(5)
	ds_write_b16 v8, v232 offset:17408
	ds_write_b16_d16_hi v8, v232 offset:17680
	ds_write_b16 v8, v233 offset:17952
	ds_write_b16_d16_hi v8, v233 offset:18224
	ds_write_b16 v8, v234 offset:18496
	ds_write_b16_d16_hi v8, v234 offset:18768
	ds_write_b16 v8, v235 offset:19040
	ds_write_b16_d16_hi v8, v235 offset:19312
	s_waitcnt vmcnt(4)
	ds_write_b16 v8, v236 offset:19584
	ds_write_b16_d16_hi v8, v236 offset:19856
	ds_write_b16 v8, v237 offset:20128
	ds_write_b16_d16_hi v8, v237 offset:20400
	ds_write_b16 v8, v238 offset:20672
	ds_write_b16_d16_hi v8, v238 offset:20944
	ds_write_b16 v8, v239 offset:21216
	v_or_b32_e32 v0, 15, v11
	v_mul_lo_u32 v0, v0, s11
	s_movk_i32 s0, 0x80
	v_add3_u32 v0, s45, v0, v9
	v_cmp_gt_i32_e32 vcc, s0, v100
	ds_write_b16_d16_hi v0, v239 offset:17408
	s_and_saveexec_b64 s[0:1], vcc
	s_cbranch_execz .LBB0_227
	v_lshl_add_u32 v0, v100, 1, v196
	ds_write_b16 v0, v192 offset:34816
	ds_write_b16 v0, v139 offset:35088
	ds_write_b16 v0, v139 offset:35360
	ds_write_b16 v0, v139 offset:35632
	ds_write_b16 v0, v139 offset:35904
	ds_write_b16 v0, v139 offset:36176
	ds_write_b16 v0, v139 offset:36448
	ds_write_b16 v0, v139 offset:36720
	ds_write_b16 v0, v139 offset:36992
	ds_write_b16 v0, v139 offset:37264
	ds_write_b16 v0, v139 offset:37536
	ds_write_b16 v0, v139 offset:37808
	ds_write_b16 v0, v139 offset:38080
	ds_write_b16 v0, v139 offset:38352
	ds_write_b16 v0, v139 offset:38624
	ds_write_b16 v0, v139 offset:38896

;   __device__ __forceinline__ bf16* h() const { unsigned o_ = (unsigned)(OFF_h); asm volatile("" : "+s"(o_)); return (bf16*)(ws + o_); }
;   __device__ __forceinline__ bf16* U() const { unsigned o_ = (unsigned)(OFF_U); asm volatile("" : "+s"(o_)); return (bf16*)(ws + o_); }
; #define UNPK8(v, f) { f[0] = lo16(v.x); f[1] = hi16(v.x); f[2] = lo16(v.y); f[3] = hi16(v.y); f[4] = lo16(v.z); f[5] = hi16(v.z); f[6] = lo16(v.w); f[7] = hi16(v.w); }
; __device__ void gla_prep_unit(const P& p, int layer, int unit, char* smem) {
;     ...
;   uint4 qv_pre, kv_pre;
;   {
;     const int t = tid >> 2, d0 = (tid & 3) * 8;
;     qv_pre = *(const uint4*)(p.U() + TROW(t) * US + C_GQ + h * 32 + d0);
;     kv_pre = *(const uint4*)(p.U() + TROW(t) * US + C_GK + h * 32 + d0);
;   }
;   __syncthreads();
;   {
;     const int t = tid >> 2, d0 = (tid & 3) * 8;
;     const bf16* cp = p.U() + TROW(t) * US + C_GC;
;     const uint4 c0 = *(const uint4*)cp, c1 = *(const uint4*)(cp + 8);
;     float cv[16];
;     { float f[8]; UNPK8(c0, f);
; #pragma unroll
;       for (int i = 0; i < 8; ++i) cv[i] = f[i];
;       UNPK8(c1, f);
; #pragma unroll
;       for (int i = 0; i < 8; ++i) cv[8 + i] = f[i]; }
;     const float* wg = p.gla_wg + (size_t)layer * 16 * 128 + h * 32 + d0;
;     float acc[8];
;     {
;       const float4 b0 = *(const float4*)(p.gla_bg + layer * 128 + h * 32 + d0), b1 = *(const float4*)(p.gla_bg + layer * 128 + h * 32 + d0 + 4);
;       acc[0] = b0.x; acc[1] = b0.y; acc[2] = b0.z; acc[3] = b0.w; acc[4] = b1.x; acc[5] = b1.y; acc[6] = b1.z; acc[7] = b1.w;
;     }
; #pragma unroll
;     for (int rr = 0; rr < 16; ++rr) {
;       const float4 w0 = *(const float4*)(wg + rr * 128), w1 = *(const float4*)(wg + rr * 128 + 4);
;       acc[0] += cv[rr] * w0.x; acc[1] += cv[rr] * w0.y; acc[2] += cv[rr] * w0.z; acc[3] += cv[rr] * w0.w;
;       acc[4] += cv[rr] * w1.x; acc[5] += cv[rr] * w1.y; acc[6] += cv[rr] * w1.z; acc[7] += cv[rr] * w1.w;
;     }
.LBB0_250:
	s_mul_i32 s0, s33, 0xfc1
	s_lshr_b32 s1, s0, 18
	s_mulk_i32 s1, 0x41
	s_sub_i32 s2, s33, s1
	s_bfe_u32 s22, s0, 0x20012
	s_lshr_b32 s0, s0, 20
	s_lshl_b32 s3, s2, 7
	s_mul_i32 s1, s0, 0x2010
	s_and_b32 s3, s3, 0xff80
	v_mov_b32_e32 v30, v136
	s_add_i32 s19, s3, s1
	s_mul_i32 s20, s0, 0x70
	s_mov_b32 s0, 0x6180000
	s_addk_i32 s19, 0xff90
	s_addk_i32 s20, 0x4020
	s_add_u32 s0, s76, s0
	s_addc_u32 s1, s77, 0
	s_and_b32 s2, s2, 0xffff
	v_ashrrev_i32_e32 v31, 2, v30
	s_cmp_eq_u32 s2, 0
	v_lshlrev_b32_e32 v0, 3, v30
	s_cselect_b64 s[14:15], -1, 0
	v_cmp_gt_i32_e32 vcc, s44, v31
	v_and_b32_e32 v32, 24, v0
	s_and_b64 vcc, s[14:15], vcc
	v_mov_b32_e32 v0, s19
	v_mov_b32_e32 v1, s20
	v_cndmask_b32_e32 v0, v0, v1, vcc
	v_add_u32_e32 v33, v0, v31
	v_mov_b64_e32 v[0:1], s[0:1]
	v_mad_i64_i32 v[0:1], s[0:1], v33, s54, v[0:1]
	s_lshl_b32 s96, s22, 6
	v_lshl_add_u64 v[0:1], v[0:1], 0, s[96:97]
	v_lshlrev_b32_e32 v138, 1, v32
	v_lshl_add_u64 v[0:1], v[0:1], 0, v[138:139]
	s_mov_b32 s0, 0x6180000
	global_load_dwordx4 v[0:3], v[0:1], off offset:1536
	s_add_u32 s0, s76, s0
	s_addc_u32 s1, s77, 0
	v_mov_b64_e32 v[4:5], s[0:1]
	v_mad_i64_i32 v[4:5], s[0:1], v33, s54, v[4:5]
	v_lshl_add_u64 v[4:5], v[4:5], 0, s[96:97]
	v_lshl_add_u64 v[4:5], v[4:5], 0, v[138:139]
	s_mov_b32 s0, 0x6180000
	global_load_dwordx4 v[4:7], v[4:5], off offset:1792
	s_barrier
	s_add_u32 s0, s76, s0
	s_addc_u32 s1, s77, 0
	v_mov_b64_e32 v[8:9], s[0:1]
	v_mad_i64_i32 v[12:13], s[0:1], v33, s54, v[8:9]
	global_load_dwordx4 v[8:11], v[12:13], off offset:3088
	s_nop 0
	global_load_dwordx4 v[12:15], v[12:13], off offset:3072
	s_lshl_b32 s21, s22, 7
	s_add_u32 s0, s62, s21
	s_addc_u32 s1, s63, 0
	s_add_u32 s2, s56, s21
	v_lshlrev_b32_e32 v26, 2, v32
	s_addc_u32 s3, s66, 0
	v_mov_b32_e32 v27, v139
	v_lshl_add_u64 v[18:19], s[0:1], 0, v[26:27]
	s_waitcnt vmcnt(1)
	v_lshlrev_b32_e32 v28, 16, v8
	s_waitcnt vmcnt(0)
	v_lshlrev_b32_e32 v42, 16, v12
	v_and_b32_e32 v43, 0xffff0000, v12
	v_lshlrev_b32_e32 v44, 16, v13
	v_and_b32_e32 v45, 0xffff0000, v13
	v_lshlrev_b32_e32 v46, 16, v14
	v_and_b32_e32 v47, 0xffff0000, v14
	v_lshlrev_b32_e32 v22, 16, v15
	v_and_b32_e32 v23, 0xffff0000, v15
	v_and_b32_e32 v29, 0xffff0000, v8
	v_lshlrev_b32_e32 v20, 16, v9
	v_and_b32_e32 v21, 0xffff0000, v9
	v_lshlrev_b32_e32 v16, 16, v10
	v_and_b32_e32 v17, 0xffff0000, v10
	v_lshlrev_b32_e32 v24, 16, v11
	v_and_b32_e32 v25, 0xffff0000, v11
	global_load_dwordx4 v[8:11], v26, s[2:3] offset:16
	global_load_dwordx4 v[12:15], v26, s[2:3]
	global_load_dwordx4 v[34:37], v26, s[0:1] offset:16
	global_load_dwordx4 v[38:41], v26, s[0:1]
	s_mov_b32 s2, 0x3d800000
	s_waitcnt vmcnt(1)
	v_fma_f32 v50, v34, v42, v8
	s_waitcnt vmcnt(0)
	v_fma_f32 v27, v38, v42, v12
	v_fma_f32 v12, v39, v42, v13
	v_fma_f32 v14, v40, v42, v14
	v_fmac_f32_e32 v15, v41, v42
	v_fma_f32 v51, v35, v42, v9
	v_fma_f32 v10, v36, v42, v10
	v_fmac_f32_e32 v11, v37, v42
	global_load_dwordx4 v[34:37], v26, s[0:1] offset:528
	global_load_dwordx4 v[38:41], v26, s[0:1] offset:512
	s_waitcnt vmcnt(1)
	v_fmac_f32_e32 v50, v34, v43
	s_waitcnt vmcnt(0)
	v_fmac_f32_e32 v27, v38, v43
	v_fmac_f32_e32 v12, v39, v43
	v_fmac_f32_e32 v14, v40, v43
	v_fmac_f32_e32 v15, v41, v43
	v_fmac_f32_e32 v51, v35, v43
	v_fmac_f32_e32 v10, v36, v43
	v_fmac_f32_e32 v11, v37, v43
	global_load_dwordx4 v[34:37], v26, s[0:1] offset:1040
	global_load_dwordx4 v[38:41], v26, s[0:1] offset:1024
	s_waitcnt vmcnt(1)
	v_fmac_f32_e32 v50, v34, v44
	s_waitcnt vmcnt(0)
	v_fmac_f32_e32 v27, v38, v44
	v_fmac_f32_e32 v12, v39, v44
	v_fmac_f32_e32 v14, v40, v44
	v_fmac_f32_e32 v15, v41, v44
	v_fmac_f32_e32 v51, v35, v44
	v_fmac_f32_e32 v10, v36, v44
	v_fmac_f32_e32 v11, v37, v44
	global_load_dwordx4 v[34:37], v26, s[0:1] offset:1552
	global_load_dwordx4 v[38:41], v26, s[0:1] offset:1536
	s_waitcnt vmcnt(1)
	v_fmac_f32_e32 v50, v34, v45
	s_waitcnt vmcnt(0)
	v_fmac_f32_e32 v27, v38, v45
	v_fmac_f32_e32 v12, v39, v45
	v_fmac_f32_e32 v14, v40, v45
	v_fmac_f32_e32 v15, v41, v45
	v_fmac_f32_e32 v51, v35, v45
	v_fmac_f32_e32 v10, v36, v45
	v_fmac_f32_e32 v11, v37, v45
	global_load_dwordx4 v[34:37], v26, s[0:1] offset:2064
	global_load_dwordx4 v[38:41], v26, s[0:1] offset:2048
	s_waitcnt vmcnt(1)
	v_fmac_f32_e32 v50, v34, v46
	s_waitcnt vmcnt(0)
	v_fmac_f32_e32 v27, v38, v46
	v_fmac_f32_e32 v12, v39, v46
	v_fmac_f32_e32 v14, v40, v46
	v_fmac_f32_e32 v15, v41, v46
	v_fmac_f32_e32 v51, v35, v46
	v_fmac_f32_e32 v10, v36, v46
	v_fmac_f32_e32 v11, v37, v46
	global_load_dwordx4 v[34:37], v26, s[0:1] offset:2576
	global_load_dwordx4 v[38:41], v26, s[0:1] offset:2560
	s_waitcnt vmcnt(1)
	v_fmac_f32_e32 v50, v34, v47
	s_waitcnt vmcnt(0)
	v_fmac_f32_e32 v27, v38, v47
	v_fmac_f32_e32 v12, v39, v47
	v_fmac_f32_e32 v14, v40, v47
	v_fmac_f32_e32 v15, v41, v47
	v_fmac_f32_e32 v51, v35, v47
	v_fmac_f32_e32 v10, v36, v47
	v_fmac_f32_e32 v11, v37, v47
	global_load_dwordx4 v[34:37], v26, s[0:1] offset:3088
	global_load_dwordx4 v[38:41], v26, s[0:1] offset:3072
	global_load_dwordx4 v[42:45], v26, s[0:1] offset:3600
	global_load_dwordx4 v[46:49], v26, s[0:1] offset:3584
	s_mov_b64 s[0:1], 0x1000
	s_waitcnt vmcnt(2)
	v_mov_b32_e32 v8, v39
	s_waitcnt vmcnt(0)
; __device__ void gla_prep_unit(const P& p, int layer, int unit, char* smem) {
;     ...
; #pragma unroll
;     for (int rr = 0; rr < 16; ++rr) {
;       const float4 w0 = *(const float4*)(wg + rr * 128), w1 = *(const float4*)(wg + rr * 128 + 4);
;       acc[0] += cv[rr] * w0.x; acc[1] += cv[rr] * w0.y; acc[2] += cv[rr] * w0.z; acc[3] += cv[rr] * w0.w;
;       acc[4] += cv[rr] * w1.x; acc[5] += cv[rr] * w1.y; acc[6] += cv[rr] * w1.z; acc[7] += cv[rr] * w1.w;
;     }
	v_mov_b32_e32 v9, v47
	v_pk_mul_f32 v[8:9], v[8:9], v[22:23]
	v_mov_b32_e32 v39, v46
	v_add_f32_e32 v8, v12, v8
	v_add_f32_e32 v46, v8, v9
	v_mov_b32_e32 v8, v40
	v_mov_b32_e32 v9, v48
	v_pk_mul_f32 v[8:9], v[8:9], v[22:23]
	v_mov_b32_e32 v48, v41
	v_add_f32_e32 v8, v14, v8
	v_add_f32_e32 v14, v8, v9
	v_pk_mul_f32 v[8:9], v[48:49], v[22:23]
	v_pk_mul_f32 v[12:13], v[38:39], v[22:23]
	v_add_f32_e32 v8, v15, v8
	v_add_f32_e32 v15, v8, v9
	v_mov_b32_e32 v8, v34
	v_mov_b32_e32 v9, v42
	v_pk_mul_f32 v[8:9], v[8:9], v[22:23]
	v_mov_b32_e32 v42, v35
	v_add_f32_e32 v8, v50, v8
	v_add_f32_e32 v47, v8, v9
	v_pk_mul_f32 v[8:9], v[42:43], v[22:23]
	v_add_f32_e32 v12, v27, v12
	v_add_f32_e32 v8, v51, v8
	v_add_f32_e32 v48, v8, v9
	v_mov_b32_e32 v8, v36
	v_mov_b32_e32 v9, v44
	v_pk_mul_f32 v[8:9], v[8:9], v[22:23]
	v_mov_b32_e32 v44, v37
	v_add_f32_e32 v8, v10, v8
	v_add_f32_e32 v49, v8, v9
	v_pk_mul_f32 v[8:9], v[44:45], v[22:23]
	v_add_co_u32_e32 v22, vcc, s10, v18
	v_add_f32_e32 v8, v11, v8
	v_add_f32_e32 v50, v8, v9
	v_lshl_add_u64 v[8:9], v[18:19], 0, s[0:1]
	v_addc_co_u32_e32 v23, vcc, 0, v19, vcc
	s_mov_b64 s[0:1], 0x1200
	v_add_f32_e32 v27, v12, v13
	global_load_dwordx4 v[10:13], v[22:23], off
	global_load_dwordx4 v[34:37], v[8:9], off offset:16
	v_lshl_add_u64 v[8:9], v[18:19], 0, s[0:1]
	global_load_dwordx4 v[38:41], v[22:23], off offset:512
	global_load_dwordx4 v[42:45], v[8:9], off offset:16
	s_mov_b64 s[0:1], 0x1400
	s_waitcnt vmcnt(3)
	v_mov_b32_e32 v8, v11
	s_waitcnt vmcnt(1)
	v_mov_b32_e32 v9, v39
	v_pk_mul_f32 v[8:9], v[8:9], v[28:29]
	v_mov_b32_e32 v11, v38
	v_add_f32_e32 v8, v46, v8
	v_add_f32_e32 v46, v8, v9
	v_mov_b32_e32 v8, v12
	v_mov_b32_e32 v9, v40
	v_pk_mul_f32 v[8:9], v[8:9], v[28:29]
	v_mov_b32_e32 v40, v13
	v_add_f32_e32 v8, v14, v8
	v_add_f32_e32 v51, v8, v9
	v_pk_mul_f32 v[8:9], v[40:41], v[28:29]
	v_pk_mul_f32 v[10:11], v[10:11], v[28:29]
	v_add_f32_e32 v8, v15, v8
	v_add_f32_e32 v52, v8, v9
	v_mov_b32_e32 v8, v34
	s_waitcnt vmcnt(0)
	v_mov_b32_e32 v9, v42
	v_pk_mul_f32 v[8:9], v[8:9], v[28:29]
	v_mov_b32_e32 v42, v35
	v_add_f32_e32 v8, v47, v8
	v_add_f32_e32 v47, v8, v9
	v_pk_mul_f32 v[8:9], v[42:43], v[28:29]
	v_add_f32_e32 v10, v27, v10
	v_add_f32_e32 v8, v48, v8
	v_add_f32_e32 v42, v8, v9
	v_mov_b32_e32 v8, v36
	v_mov_b32_e32 v9, v44
	v_pk_mul_f32 v[8:9], v[8:9], v[28:29]
	v_mov_b32_e32 v44, v37
	v_add_f32_e32 v8, v49, v8
	v_add_f32_e32 v43, v8, v9
	v_pk_mul_f32 v[8:9], v[44:45], v[28:29]
	v_lshl_add_u64 v[12:13], v[18:19], 0, s[0:1]
	v_add_f32_e32 v8, v50, v8
	s_mov_b64 s[0:1], 0x1600
	v_add_f32_e32 v27, v10, v11
	v_add_f32_e32 v44, v8, v9
	global_load_dwordx4 v[8:11], v[22:23], off offset:1024
	s_nop 0
	global_load_dwordx4 v[12:15], v[12:13], off offset:16
	v_lshl_add_u64 v[28:29], v[18:19], 0, s[0:1]
	global_load_dwordx4 v[34:37], v[22:23], off offset:1536
	global_load_dwordx4 v[38:41], v[28:29], off offset:16
	s_mov_b64 s[0:1], 0x1800
	s_waitcnt vmcnt(3)
	v_mov_b32_e32 v28, v9
	s_waitcnt vmcnt(1)
	v_mov_b32_e32 v9, v34
	v_pk_mul_f32 v[8:9], v[8:9], v[20:21]
	v_mov_b32_e32 v29, v35
	v_add_f32_e32 v8, v27, v8
	v_add_f32_e32 v27, v8, v9
	v_mov_b32_e32 v8, v10
	v_mov_b32_e32 v9, v36
	v_pk_mul_f32 v[28:29], v[28:29], v[20:21]
	v_pk_mul_f32 v[8:9], v[8:9], v[20:21]
	v_add_f32_e32 v28, v46, v28
	v_add_f32_e32 v8, v51, v8
	v_mov_b32_e32 v36, v11
	v_add_f32_e32 v28, v28, v29
	v_add_f32_e32 v29, v8, v9
	v_pk_mul_f32 v[8:9], v[36:37], v[20:21]
	s_nop 0
	v_add_f32_e32 v8, v52, v8
	v_add_f32_e32 v34, v8, v9
	v_mov_b32_e32 v8, v12
	s_waitcnt vmcnt(0)
	v_mov_b32_e32 v9, v38
	v_pk_mul_f32 v[8:9], v[8:9], v[20:21]
	v_mov_b32_e32 v38, v13
	v_add_f32_e32 v8, v47, v8
	v_add_f32_e32 v35, v8, v9
	v_pk_mul_f32 v[8:9], v[38:39], v[20:21]
	v_lshl_add_u64 v[12:13], v[18:19], 0, s[0:1]
	v_add_f32_e32 v8, v42, v8
	v_add_f32_e32 v46, v8, v9
	v_mov_b32_e32 v8, v14
	v_mov_b32_e32 v9, v40
	v_pk_mul_f32 v[8:9], v[8:9], v[20:21]
	v_mov_b32_e32 v40, v15
	v_add_f32_e32 v8, v43, v8
	v_add_f32_e32 v47, v8, v9
	v_pk_mul_f32 v[8:9], v[40:41], v[20:21]
	s_mov_b64 s[0:1], 0x1a00
	v_add_f32_e32 v8, v44, v8
	v_add_f32_e32 v48, v8, v9
	global_load_dwordx4 v[8:11], v[22:23], off offset:2048
	s_nop 0
	global_load_dwordx4 v[12:15], v[12:13], off offset:16
	v_lshl_add_u64 v[20:21], v[18:19], 0, s[0:1]
	global_load_dwordx4 v[38:41], v[22:23], off offset:2560
	global_load_dwordx4 v[42:45], v[20:21], off offset:16
	s_mov_b64 s[0:1], 0x1c00
	s_waitcnt vmcnt(3)
	v_mov_b32_e32 v20, v9
	s_waitcnt vmcnt(1)
	v_mov_b32_e32 v9, v38
	v_pk_mul_f32 v[8:9], v[8:9], v[16:17]
	v_mov_b32_e32 v21, v39
	v_add_f32_e32 v8, v27, v8
	v_add_f32_e32 v36, v8, v9
	v_mov_b32_e32 v8, v10
	v_mov_b32_e32 v9, v40
	v_pk_mul_f32 v[8:9], v[8:9], v[16:17]
	v_mov_b32_e32 v40, v11
	v_add_f32_e32 v8, v29, v8
	v_add_f32_e32 v37, v8, v9
	v_pk_mul_f32 v[8:9], v[40:41], v[16:17]
	v_pk_mul_f32 v[20:21], v[20:21], v[16:17]
	v_add_f32_e32 v8, v34, v8
	v_add_f32_e32 v34, v8, v9
	v_mov_b32_e32 v8, v12
	s_waitcnt vmcnt(0)
	v_mov_b32_e32 v9, v42
	v_pk_mul_f32 v[8:9], v[8:9], v[16:17]
	v_mov_b32_e32 v42, v13
	v_add_f32_e32 v8, v35, v8
	v_add_f32_e32 v35, v8, v9
	v_pk_mul_f32 v[8:9], v[42:43], v[16:17]
	v_add_f32_e32 v20, v28, v20
	v_add_f32_e32 v8, v46, v8
	v_add_f32_e32 v27, v8, v9
	v_mov_b32_e32 v8, v14
	v_mov_b32_e32 v9, v44
	v_pk_mul_f32 v[8:9], v[8:9], v[16:17]
	v_mov_b32_e32 v44, v15
	v_add_f32_e32 v8, v47, v8
	v_add_f32_e32 v28, v8, v9
	v_pk_mul_f32 v[8:9], v[44:45], v[16:17]
	v_add_f32_e32 v38, v20, v21
	v_add_f32_e32 v8, v48, v8
	v_add_f32_e32 v29, v8, v9
	v_lshl_add_u64 v[8:9], v[18:19], 0, s[0:1]
	s_mov_b64 s[0:1], 0x1e00
	v_lshl_add_u64 v[20:21], v[18:19], 0, s[0:1]
	global_load_dwordx4 v[12:15], v[22:23], off offset:3072
	s_nop 0
	global_load_dwordx4 v[8:11], v[8:9], off offset:16
	s_nop 0
	global_load_dwordx4 v[16:19], v[22:23], off offset:3584
	s_nop 0
	global_load_dwordx4 v[20:23], v[20:21], off offset:16
	s_movk_i32 s0, 0x84
	s_waitcnt vmcnt(3)
; __device__ __forceinline__ float logsig(float x) { return fminf(x, 0.f) - __logf(1.f + __expf(-fabsf(x))); }
; __device__ void gla_prep_unit(const P& p, int layer, int unit, char* smem) {
;     ...
; #pragma unroll
;     for (int rr = 0; rr < 16; ++rr) {
;       const float4 w0 = *(const float4*)(wg + rr * 128), w1 = *(const float4*)(wg + rr * 128 + 4);
;       acc[0] += cv[rr] * w0.x; acc[1] += cv[rr] * w0.y; acc[2] += cv[rr] * w0.z; acc[3] += cv[rr] * w0.w;
;       acc[4] += cv[rr] * w1.x; acc[5] += cv[rr] * w1.y; acc[6] += cv[rr] * w1.z; acc[7] += cv[rr] * w1.w;
;     }
; #pragma unroll
;     for (int i = 0; i < 8; ++i) la[t * 33 + d0 + i] = logsig(acc[i]) * (1.f / 16.f);
	v_mov_b32_e32 v40, v13
	s_waitcnt vmcnt(1)
	v_mov_b32_e32 v13, v16
	v_pk_mul_f32 v[12:13], v[12:13], v[24:25]
	v_mov_b32_e32 v41, v17
	v_add_f32_e32 v12, v36, v12
	v_add_f32_e32 v16, v12, v13
	v_mov_b32_e32 v12, v14
	v_mov_b32_e32 v13, v18
	v_pk_mul_f32 v[12:13], v[12:13], v[24:25]
	v_mov_b32_e32 v18, v15
	v_add_f32_e32 v12, v37, v12
	v_add_f32_e32 v36, v12, v13
	v_pk_mul_f32 v[12:13], v[18:19], v[24:25]
	v_pk_mul_f32 v[40:41], v[40:41], v[24:25]
	v_add_f32_e32 v12, v34, v12
	v_add_f32_e32 v18, v12, v13
	v_mov_b32_e32 v12, v8
	s_waitcnt vmcnt(0)
	v_mov_b32_e32 v13, v20
	v_pk_mul_f32 v[12:13], v[12:13], v[24:25]
	v_mov_b32_e32 v20, v9
	v_add_f32_e32 v8, v35, v12
	v_add_f32_e32 v13, v8, v13
	v_pk_mul_f32 v[8:9], v[20:21], v[24:25]
	v_add_f32_e32 v17, v38, v40
	v_add_f32_e32 v8, v27, v8
	v_add_f32_e32 v19, v8, v9
	v_mov_b32_e32 v8, v10
	v_mov_b32_e32 v9, v22
	v_pk_mul_f32 v[8:9], v[8:9], v[24:25]
	v_mov_b32_e32 v22, v11
	v_add_f32_e32 v8, v28, v8
	v_add_f32_e32 v20, v8, v9
	v_pk_mul_f32 v[8:9], v[22:23], v[24:25]
	v_add_f32_e32 v17, v17, v41
	v_add_f32_e32 v8, v29, v8
	v_add_f32_e32 v8, v8, v9
	v_mul_lo_u32 v9, v31, s0
	v_add3_u32 v12, s45, v9, v26
	v_mul_f32_e64 v9, |v16|, s43
	v_exp_f32_e32 v9, v9
	v_min_f32_e32 v10, 0, v16
	v_and_b32_e32 v16, 64, v198
	v_add_f32_e32 v9, 1.0, v9
	v_cmp_gt_f32_e32 vcc, s92, v9
	s_nop 1
	v_cndmask_b32_e64 v11, 0, 32, vcc
	v_ldexp_f32 v9, v9, v11
	v_log_f32_e32 v9, v9
	s_nop 0
	v_mul_f32_e32 v11, 0x3f317217, v9
	v_fma_f32 v11, v9, s93, -v11
	v_fmac_f32_e32 v11, 0x3377d1cf, v9
	v_fmac_f32_e32 v11, 0x3f317217, v9
	v_cmp_lt_f32_e64 s[0:1], |v9|, s49
	s_nop 1
	v_cndmask_b32_e64 v9, v9, v11, s[0:1]
	v_cndmask_b32_e32 v11, 0, v197, vcc
	v_sub_f32_e32 v14, v9, v11
	v_mul_f32_e64 v9, |v17|, s43
	v_exp_f32_e32 v9, v9
	v_min_f32_e32 v11, 0, v17
	v_and_b32_e32 v17, 63, v30
	v_cmp_gt_u32_e64 s[6:7], 8, v17
	v_add_f32_e32 v9, 1.0, v9
	v_cmp_gt_f32_e32 vcc, s92, v9
	v_cmp_gt_u32_e64 s[8:9], 16, v17
	v_cmp_gt_u32_e64 s[12:13], 32, v17
	v_cndmask_b32_e64 v15, 0, 32, vcc
	v_ldexp_f32 v9, v9, v15
	v_log_f32_e32 v9, v9
	s_nop 0
	v_mul_f32_e32 v15, 0x3f317217, v9
	v_fma_f32 v15, v9, s93, -v15
	v_fmac_f32_e32 v15, 0x3377d1cf, v9
	v_fmac_f32_e32 v15, 0x3f317217, v9
	v_cmp_lt_f32_e64 s[0:1], |v9|, s49
	s_nop 1
	v_cndmask_b32_e64 v9, v9, v15, s[0:1]
	v_cndmask_b32_e32 v15, 0, v197, vcc
	v_sub_f32_e32 v15, v9, v15
	v_mul_f32_e64 v9, |v36|, s43
	v_exp_f32_e32 v9, v9
	v_pk_add_f32 v[10:11], v[10:11], v[14:15] neg_lo:[0,1] neg_hi:[0,1]
	v_add_f32_e32 v9, 1.0, v9
	v_pk_mul_f32 v[10:11], v[10:11], s[2:3] op_sel_hi:[1,0]
	v_cmp_gt_f32_e32 vcc, s92, v9
	ds_write2_b32 v12, v10, v11 offset1:1
	v_min_f32_e32 v10, 0, v36
	v_cndmask_b32_e64 v11, 0, 32, vcc
	v_ldexp_f32 v9, v9, v11
	v_log_f32_e32 v9, v9
	s_nop 0
	v_mul_f32_e32 v11, 0x3f317217, v9
	v_fma_f32 v11, v9, s93, -v11
	v_fmac_f32_e32 v11, 0x3377d1cf, v9
	v_fmac_f32_e32 v11, 0x3f317217, v9
	v_cmp_lt_f32_e64 s[0:1], |v9|, s49
	s_nop 1
	v_cndmask_b32_e64 v9, v9, v11, s[0:1]
	v_cndmask_b32_e32 v11, 0, v197, vcc
	v_sub_f32_e32 v14, v9, v11
	v_mul_f32_e64 v9, |v18|, s43
	v_exp_f32_e32 v9, v9
	v_min_f32_e32 v11, 0, v18
	v_subrev_u32_e32 v18, 32, v198
	v_add_f32_e32 v9, 1.0, v9
	v_cmp_gt_f32_e32 vcc, s92, v9
	s_nop 1
	v_cndmask_b32_e64 v15, 0, 32, vcc
	v_ldexp_f32 v9, v9, v15
	v_log_f32_e32 v9, v9
	s_nop 0
	v_mul_f32_e32 v15, 0x3f317217, v9
	v_fma_f32 v15, v9, s93, -v15
	v_fmac_f32_e32 v15, 0x3377d1cf, v9
	v_fmac_f32_e32 v15, 0x3f317217, v9
	v_cmp_lt_f32_e64 s[0:1], |v9|, s49
	s_nop 1
	v_cndmask_b32_e64 v9, v9, v15, s[0:1]
	v_cndmask_b32_e32 v15, 0, v197, vcc
	v_sub_f32_e32 v15, v9, v15
	v_mul_f32_e64 v9, |v13|, s43
	v_exp_f32_e32 v9, v9
	v_pk_add_f32 v[10:11], v[10:11], v[14:15] neg_lo:[0,1] neg_hi:[0,1]
	v_add_f32_e32 v9, 1.0, v9
	v_pk_mul_f32 v[10:11], v[10:11], s[2:3] op_sel_hi:[1,0]
	v_cmp_gt_f32_e32 vcc, s92, v9
	ds_write2_b32 v12, v10, v11 offset0:2 offset1:3
	v_min_f32_e32 v10, 0, v13
	v_cndmask_b32_e64 v11, 0, 32, vcc
	v_ldexp_f32 v9, v9, v11
	v_log_f32_e32 v9, v9
	s_nop 0
	v_mul_f32_e32 v11, 0x3f317217, v9
	v_fma_f32 v11, v9, s93, -v11
	v_fmac_f32_e32 v11, 0x3377d1cf, v9
	v_fmac_f32_e32 v11, 0x3f317217, v9
	v_cmp_lt_f32_e64 s[0:1], |v9|, s49
	s_nop 1
	v_cndmask_b32_e64 v9, v9, v11, s[0:1]
	v_cndmask_b32_e32 v11, 0, v197, vcc
	v_sub_f32_e32 v14, v9, v11
	v_mul_f32_e64 v9, |v19|, s43
	v_exp_f32_e32 v9, v9
	v_min_f32_e32 v11, 0, v19
	v_add_f32_e32 v9, 1.0, v9
	v_cmp_gt_f32_e32 vcc, s92, v9
	s_nop 1
	v_cndmask_b32_e64 v13, 0, 32, vcc
	v_ldexp_f32 v9, v9, v13
	v_log_f32_e32 v9, v9
	s_nop 0
	v_mul_f32_e32 v13, 0x3f317217, v9
	v_fma_f32 v13, v9, s93, -v13
	v_fmac_f32_e32 v13, 0x3377d1cf, v9
	v_fmac_f32_e32 v13, 0x3f317217, v9
	v_cmp_lt_f32_e64 s[0:1], |v9|, s49
	s_nop 1
	v_cndmask_b32_e64 v9, v9, v13, s[0:1]
	v_cndmask_b32_e32 v13, 0, v197, vcc
	v_sub_f32_e32 v15, v9, v13
	v_mul_f32_e64 v9, |v20|, s43
	v_exp_f32_e32 v9, v9
	v_pk_add_f32 v[10:11], v[10:11], v[14:15] neg_lo:[0,1] neg_hi:[0,1]
	v_add_u32_e32 v13, -4, v198
	v_pk_mul_f32 v[10:11], v[10:11], s[2:3] op_sel_hi:[1,0]
	v_add_f32_e32 v9, 1.0, v9
	v_cmp_gt_f32_e32 vcc, s92, v9
	ds_write2_b32 v12, v10, v11 offset0:4 offset1:5
	v_min_f32_e32 v10, 0, v20
	v_cndmask_b32_e64 v11, 0, 32, vcc
	v_ldexp_f32 v9, v9, v11
	v_log_f32_e32 v9, v9
	s_nop 0
	v_mul_f32_e32 v11, 0x3f317217, v9
	v_fma_f32 v11, v9, s93, -v11
	v_fmac_f32_e32 v11, 0x3377d1cf, v9
	v_fmac_f32_e32 v11, 0x3f317217, v9
	v_cmp_lt_f32_e64 s[0:1], |v9|, s49
	s_nop 1
	v_cndmask_b32_e64 v9, v9, v11, s[0:1]
	v_cndmask_b32_e32 v11, 0, v197, vcc
	v_sub_f32_e32 v14, v9, v11
	v_min_f32_e32 v11, 0, v8
	v_mul_f32_e64 v8, |v8|, s43
	v_exp_f32_e32 v8, v8
	s_nop 0
	v_add_f32_e32 v8, 1.0, v8
; __device__ void gla_prep_unit(const P& p, int layer, int unit, char* smem) {
;     ...
; #pragma unroll
;   for (int i = 0; i < 4; ++i) {
;     const int d = 4 * w + i;
;     const float v0 = la[(2 * lane) * 33 + d], v1 = la[(2 * lane + 1) * 33 + d];
;     const float s = v0 + v1;
;     const float incl = scan_add(s, lane);
;     la[(2 * lane) * 33 + d] = incl - s + v0;
;     la[(2 * lane + 1) * 33 + d] = incl;
;     if (lane == 63) cl[d] = incl;
;   }
	v_cmp_gt_f32_e32 vcc, s92, v8
	s_nop 1
	v_cndmask_b32_e64 v9, 0, 32, vcc
	v_ldexp_f32 v8, v8, v9
	v_log_f32_e32 v8, v8
	s_nop 0
	v_mul_f32_e32 v9, 0x3f317217, v8
	v_fma_f32 v9, v8, s93, -v9
	v_fmac_f32_e32 v9, 0x3377d1cf, v8
	v_fmac_f32_e32 v9, 0x3f317217, v8
	v_cmp_lt_f32_e64 s[0:1], |v8|, s49
	s_nop 1
	v_cndmask_b32_e64 v8, v8, v9, s[0:1]
	v_cndmask_b32_e32 v9, 0, v197, vcc
	v_sub_f32_e32 v15, v8, v9
	v_pk_add_f32 v[8:9], v[10:11], v[14:15] neg_lo:[0,1] neg_hi:[0,1]
	v_add_u32_e32 v14, -8, v198
	v_pk_mul_f32 v[8:9], v[8:9], s[2:3] op_sel_hi:[1,0]
	v_cmp_lt_i32_e64 s[4:5], v14, v16
	v_add_u32_e32 v15, -16, v198
	ds_write2_b32 v12, v8, v9 offset0:6 offset1:7
	v_ashrrev_i32_e32 v8, 4, v30
	s_movk_i32 s0, 0x108
	v_add_u32_e32 v10, -1, v198
	v_add_u32_e32 v11, -2, v198
	v_cndmask_b32_e64 v14, v14, v198, s[4:5]
	v_cmp_lt_i32_e64 s[4:5], v15, v16
	v_and_b32_e32 v20, -4, v8
	v_mad_u32_u24 v9, v17, s0, v196
	v_cmp_lt_i32_e32 vcc, v10, v16
	v_cmp_lt_i32_e64 s[0:1], v11, v16
	v_cmp_lt_i32_e64 s[2:3], v13, v16
	v_cndmask_b32_e64 v15, v15, v198, s[4:5]
	v_cmp_lt_i32_e64 s[4:5], v18, v16
	v_cndmask_b32_e32 v10, v10, v198, vcc
	v_cmp_eq_u32_e32 vcc, 0, v17
	v_cndmask_b32_e64 v11, v11, v198, s[0:1]
	v_cmp_gt_u32_e64 s[0:1], 2, v17
	v_cndmask_b32_e64 v13, v13, v198, s[2:3]
	v_cmp_gt_u32_e64 s[2:3], 4, v17
	v_cndmask_b32_e64 v16, v18, v198, s[4:5]
	v_cmp_eq_u32_e64 s[4:5], 63, v17
	v_lshl_add_u32 v17, v20, 2, v9
	s_waitcnt lgkmcnt(0)
	s_barrier
	ds_read2_b32 v[18:19], v17 offset1:33
	v_lshlrev_b32_e32 v10, 2, v10
	v_lshlrev_b32_e32 v11, 2, v11
	v_lshlrev_b32_e32 v13, 2, v13
	v_lshlrev_b32_e32 v14, 2, v14
	s_waitcnt lgkmcnt(0)
	v_add_f32_e32 v21, v18, v19
	ds_bpermute_b32 v19, v10, v21
	v_lshlrev_b32_e32 v15, 2, v15
	v_lshlrev_b32_e32 v16, 2, v16
	s_waitcnt lgkmcnt(0)
	v_add_f32_e32 v19, v21, v19
	v_cndmask_b32_e32 v19, v19, v21, vcc
	ds_bpermute_b32 v22, v11, v19
	s_waitcnt lgkmcnt(0)
	v_add_f32_e32 v22, v19, v22
	v_cndmask_b32_e64 v19, v22, v19, s[0:1]
	ds_bpermute_b32 v22, v13, v19
	s_waitcnt lgkmcnt(0)
	v_add_f32_e32 v22, v19, v22
	v_cndmask_b32_e64 v19, v22, v19, s[2:3]
	ds_bpermute_b32 v22, v14, v19
	s_waitcnt lgkmcnt(0)
	v_add_f32_e32 v22, v19, v22
	v_cndmask_b32_e64 v19, v22, v19, s[6:7]
	ds_bpermute_b32 v22, v15, v19
	s_waitcnt lgkmcnt(0)
	v_add_f32_e32 v22, v19, v22
	v_cndmask_b32_e64 v22, v22, v19, s[8:9]
	ds_bpermute_b32 v19, v16, v22
	s_waitcnt lgkmcnt(0)
	v_add_f32_e32 v19, v22, v19
	v_cndmask_b32_e64 v22, v19, v22, s[12:13]
	v_sub_f32_e32 v21, v22, v21
	v_add_f32_e32 v18, v18, v21
	ds_write2_b32 v17, v18, v22 offset1:33
	v_lshl_add_u32 v18, v20, 2, v196
	s_and_saveexec_b64 s[16:17], s[4:5]
	ds_write_b32 v18, v19 offset:16896
	s_or_b64 exec, exec, s[16:17]
	ds_read2_b32 v[20:21], v17 offset0:1 offset1:34
	s_waitcnt lgkmcnt(0)
	v_add_f32_e32 v21, v20, v21
	ds_bpermute_b32 v19, v10, v21
	s_waitcnt lgkmcnt(0)
	v_add_f32_e32 v19, v21, v19
	v_cndmask_b32_e32 v19, v19, v21, vcc
	ds_bpermute_b32 v22, v11, v19
	s_waitcnt lgkmcnt(0)
	v_add_f32_e32 v22, v19, v22
	v_cndmask_b32_e64 v19, v22, v19, s[0:1]
	ds_bpermute_b32 v22, v13, v19
	s_waitcnt lgkmcnt(0)
	v_add_f32_e32 v22, v19, v22
	v_cndmask_b32_e64 v19, v22, v19, s[2:3]
	ds_bpermute_b32 v22, v14, v19
	s_waitcnt lgkmcnt(0)
	v_add_f32_e32 v22, v19, v22
	v_cndmask_b32_e64 v19, v22, v19, s[6:7]
	ds_bpermute_b32 v22, v15, v19
	s_waitcnt lgkmcnt(0)
	v_add_f32_e32 v22, v19, v22
	v_cndmask_b32_e64 v22, v22, v19, s[8:9]
	ds_bpermute_b32 v19, v16, v22
	s_waitcnt lgkmcnt(0)
	v_add_f32_e32 v19, v22, v19
	v_cndmask_b32_e64 v22, v19, v22, s[12:13]
	v_sub_f32_e32 v21, v22, v21
	v_add_f32_e32 v20, v20, v21
	ds_write2_b32 v17, v20, v22 offset0:1 offset1:34
	s_and_saveexec_b64 s[16:17], s[4:5]
	ds_write_b32 v18, v19 offset:16900
	s_or_b64 exec, exec, s[16:17]
	ds_read2_b32 v[20:21], v17 offset0:2 offset1:35
	s_waitcnt lgkmcnt(0)
	v_add_f32_e32 v21, v20, v21
	ds_bpermute_b32 v19, v10, v21
	s_waitcnt lgkmcnt(0)
	v_add_f32_e32 v19, v21, v19
	v_cndmask_b32_e32 v19, v19, v21, vcc
	ds_bpermute_b32 v22, v11, v19
	s_waitcnt lgkmcnt(0)
	v_add_f32_e32 v22, v19, v22
	v_cndmask_b32_e64 v19, v22, v19, s[0:1]
	ds_bpermute_b32 v22, v13, v19
	s_waitcnt lgkmcnt(0)
	v_add_f32_e32 v22, v19, v22
	v_cndmask_b32_e64 v19, v22, v19, s[2:3]
	ds_bpermute_b32 v22, v14, v19
	s_waitcnt lgkmcnt(0)
	v_add_f32_e32 v22, v19, v22
	v_cndmask_b32_e64 v19, v22, v19, s[6:7]
	ds_bpermute_b32 v22, v15, v19
	s_waitcnt lgkmcnt(0)
	v_add_f32_e32 v22, v19, v22
	v_cndmask_b32_e64 v22, v22, v19, s[8:9]
	ds_bpermute_b32 v19, v16, v22
	s_waitcnt lgkmcnt(0)
	v_add_f32_e32 v19, v22, v19
	v_cndmask_b32_e64 v22, v19, v22, s[12:13]
	v_sub_f32_e32 v21, v22, v21
	v_add_f32_e32 v20, v20, v21
	ds_write2_b32 v17, v20, v22 offset0:2 offset1:35
	s_and_saveexec_b64 s[16:17], s[4:5]
	ds_write_b32 v18, v19 offset:16904
	s_or_b64 exec, exec, s[16:17]
	v_or_b32_e32 v8, 3, v8
	v_lshl_add_u32 v17, v8, 2, v9
	ds_read2_b32 v[18:19], v17 offset1:33
	s_waitcnt lgkmcnt(0)
	v_add_f32_e32 v19, v18, v19
	ds_bpermute_b32 v9, v10, v19
	s_waitcnt lgkmcnt(0)
	v_add_f32_e32 v9, v19, v9
	v_cndmask_b32_e32 v9, v9, v19, vcc
	ds_bpermute_b32 v10, v11, v9
	s_waitcnt lgkmcnt(0)
	v_add_f32_e32 v10, v9, v10
	v_cndmask_b32_e64 v9, v10, v9, s[0:1]
	ds_bpermute_b32 v10, v13, v9
	s_waitcnt lgkmcnt(0)
	v_add_f32_e32 v10, v9, v10
	v_cndmask_b32_e64 v9, v10, v9, s[2:3]
	ds_bpermute_b32 v10, v14, v9
	s_lshl_b32 s2, s22, 5
	s_waitcnt lgkmcnt(0)
	v_add_f32_e32 v10, v9, v10
	v_cndmask_b32_e64 v9, v10, v9, s[6:7]
	ds_bpermute_b32 v10, v15, v9
	s_waitcnt lgkmcnt(0)
	v_add_f32_e32 v10, v9, v10
	v_cndmask_b32_e64 v10, v10, v9, s[8:9]
	ds_bpermute_b32 v9, v16, v10
	s_waitcnt lgkmcnt(0)
	v_add_f32_e32 v9, v10, v9
	v_cndmask_b32_e64 v10, v9, v10, s[12:13]
	v_sub_f32_e32 v11, v10, v19
	v_add_f32_e32 v11, v18, v11
	ds_write2_b32 v17, v11, v10 offset1:33
	s_and_saveexec_b64 s[0:1], s[4:5]
	v_lshl_add_u32 v8, v8, 2, v196
	ds_write_b32 v8, v9 offset:16896
	s_or_b64 exec, exec, s[0:1]
	v_mad_i64_i32 v[8:9], s[0:1], v33, s54, 0
	s_mov_b32 s0, 0x6180000
	s_waitcnt lgkmcnt(0)
	s_barrier
;   __device__ __forceinline__ bf16* h() const { unsigned o_ = (unsigned)(OFF_h); asm volatile("" : "+s"(o_)); return (bf16*)(ws + o_); }
;   __device__ __forceinline__ bf16* U() const { unsigned o_ = (unsigned)(OFF_U); asm volatile("" : "+s"(o_)); return (bf16*)(ws + o_); }
; #define UNPK8(v, f) { f[0] = lo16(v.x); f[1] = hi16(v.x); f[2] = lo16(v.y); f[3] = hi16(v.y); f[4] = lo16(v.z); f[5] = hi16(v.z); f[6] = lo16(v.w); f[7] = hi16(v.w); }
; __device__ void gla_prep_unit(const P& p, int layer, int unit, char* smem) {
;     ...
;   {
;     const int t = tid >> 2, d0 = (tid & 3) * 8;
;     bf16* qp = p.U() + TROW(t) * US + C_GQ + h * 32 + d0;
;     bf16* kp = p.U() + TROW(t) * US + C_GK + h * 32 + d0;
;     const uint4 qv = qv_pre, kv = kv_pre;
;     float qf[8], kf[8], qd[8], kd[8], kx8[8];
;     UNPK8(qv, qf); UNPK8(kv, kf);
; #pragma unroll
;     for (int i = 0; i < 8; ++i) {
;       const float cum = la[t * 33 + d0 + i];
;       qd[i] = qf[i] * 0.17677669529663687f * __expf(cum);
;       kd[i] = kf[i] * __expf(-cum);
;       kx8[i] = kf[i] * __expf(cl[d0 + i] - cum);
;     }
	s_add_u32 s0, s76, s0
	s_addc_u32 s1, s77, 0
	v_lshl_add_u64 v[10:11], s[0:1], 0, v[8:9]
	s_mov_b32 s0, 0x6180000
	ds_read2_b32 v[14:15], v12 offset1:1
	v_lshlrev_b32_e32 v25, 16, v2
	v_and_b32_e32 v26, 0xffff0000, v2
	v_lshlrev_b32_e32 v18, 16, v0
	v_lshlrev_b32_e32 v23, 16, v1
	s_waitcnt lgkmcnt(0)
	v_mul_f32_e32 v2, 0x3fb8aa3b, v14
	v_exp_f32_e32 v2, v2
	v_and_b32_e32 v24, 0xffff0000, v1
	v_mul_f32_e32 v1, 0x3e3504f3, v18
	v_lshlrev_b32_e32 v33, 16, v5
	v_and_b32_e32 v34, 0xffff0000, v5
	v_mul_f32_e32 v5, v1, v2
	v_mul_f32_e32 v1, 0xbfb8aa3b, v14
	v_exp_f32_e32 v1, v1
	v_and_b32_e32 v22, 0xffff0000, v0
	v_lshlrev_b32_e32 v28, 16, v4
	v_lshl_add_u32 v0, v32, 2, v196
	v_lshlrev_b32_e32 v27, 16, v3
	v_and_b32_e32 v16, 0xffff0000, v3
	v_and_b32_e32 v29, 0xffff0000, v4
	v_mul_f32_e32 v4, v1, v28
	ds_read_b128 v[18:21], v0 offset:16896
	ds_read_b128 v[0:3], v0 offset:16912
	v_lshlrev_b32_e32 v35, 16, v6
	v_and_b32_e32 v36, 0xffff0000, v6
	v_lshlrev_b32_e32 v17, 16, v7
	s_waitcnt lgkmcnt(1)
	v_sub_f32_e32 v6, v18, v14
	v_mul_f32_e32 v6, 0x3fb8aa3b, v6
	v_and_b32_e32 v13, 0xffff0000, v7
	v_exp_f32_e32 v6, v6
	v_mul_f32_e32 v7, 0x3fb8aa3b, v15
	v_exp_f32_e32 v7, v7
	v_mul_f32_e32 v25, 0x3e3504f3, v25
	v_mul_f32_e32 v14, v6, v28
	v_mul_f32_e32 v6, 0x3e3504f3, v22
	v_mul_f32_e32 v7, v6, v7
	v_mul_f32_e32 v6, 0xbfb8aa3b, v15
	v_sub_f32_e32 v15, v19, v15
	ds_read2_b32 v[18:19], v12 offset0:2 offset1:3
	v_mul_f32_e32 v22, 0x3e3504f3, v23
	v_mul_f32_e32 v15, 0x3fb8aa3b, v15
	v_exp_f32_e32 v6, v6
	v_exp_f32_e32 v15, v15
	s_waitcnt lgkmcnt(0)
	v_mul_f32_e32 v23, 0x3fb8aa3b, v18
	v_exp_f32_e32 v23, v23
	v_mul_f32_e32 v6, v6, v29
	v_mul_f32_e32 v15, v15, v29
	s_lshl_b32 s96, s2, 1
	v_mul_f32_e32 v22, v22, v23
	v_mul_f32_e32 v23, 0xbfb8aa3b, v18
	v_sub_f32_e32 v18, v20, v18
	v_mul_f32_e32 v18, 0x3fb8aa3b, v18
	v_exp_f32_e32 v18, v18
	v_exp_f32_e32 v23, v23
	s_add_u32 s0, s76, s0
	s_addc_u32 s1, s77, 0
	v_mul_f32_e32 v20, v18, v33
	v_mul_f32_e32 v18, 0x3e3504f3, v24
	v_mul_f32_e32 v24, 0x3fb8aa3b, v19
	v_exp_f32_e32 v24, v24
	v_mul_f32_e32 v23, v23, v33
	v_lshl_add_u64 v[10:11], v[10:11], 0, s[96:97]
	v_lshl_add_u64 v[8:9], s[0:1], 0, v[8:9]
	v_mul_f32_e32 v24, v18, v24
	v_mul_f32_e32 v18, 0xbfb8aa3b, v19
	v_exp_f32_e32 v18, v18
	v_lshl_add_u64 v[8:9], v[8:9], 0, s[96:97]
	v_lshl_add_u64 v[10:11], v[10:11], 0, v[138:139]
	s_mov_b32 s0, 0x6180000
	v_mul_f32_e32 v28, v18, v34
	v_sub_f32_e32 v18, v21, v19
	v_mul_f32_e32 v18, 0x3fb8aa3b, v18
	v_exp_f32_e32 v18, v18
	v_lshl_add_u64 v[8:9], v[8:9], 0, v[138:139]
	v_cvt_pk_bf16_f32 v4, v4, v6
	s_mov_b32 s2, 0x1aac3000
	v_mul_f32_e32 v21, v18, v34
	ds_read2_b32 v[18:19], v12 offset0:4 offset1:5
	s_waitcnt lgkmcnt(0)
	v_sub_f32_e32 v0, v0, v18
	v_mul_f32_e32 v29, 0x3fb8aa3b, v18
	v_mul_f32_e32 v0, 0x3fb8aa3b, v0
	v_exp_f32_e32 v29, v29
	v_exp_f32_e32 v0, v0
	v_mul_f32_e32 v25, v25, v29
	v_mul_f32_e32 v29, 0xbfb8aa3b, v18
	v_mul_f32_e32 v18, v0, v35
	v_mul_f32_e32 v0, 0x3e3504f3, v26
	v_mul_f32_e32 v26, 0x3fb8aa3b, v19
	v_exp_f32_e32 v26, v26
	v_exp_f32_e32 v29, v29
	v_mul_f32_e32 v26, v0, v26
	v_mul_f32_e32 v0, 0xbfb8aa3b, v19
	v_exp_f32_e32 v0, v0
	v_mul_f32_e32 v29, v29, v35
	v_mul_f32_e32 v33, v0, v36
	v_sub_f32_e32 v0, v1, v19
	v_mul_f32_e32 v0, 0x3fb8aa3b, v0
	v_exp_f32_e32 v0, v0
	v_cvt_pk_bf16_f32 v6, v29, v33
	s_nop 0
	v_mul_f32_e32 v19, v0, v36
	ds_read2_b32 v[0:1], v12 offset0:6 offset1:7
	v_mul_f32_e32 v12, 0x3e3504f3, v27
	s_waitcnt lgkmcnt(0)
; __device__ __forceinline__ bf16 f2bf(float f) { return (bf16)(pk2(f, 0.f) & 0xffffu); }
; template <int DK, int NE>
; __device__ __forceinline__ void local_mfma(const bf16* KxT, const bf16* VxT, float* outc, float* outn) {
;   const int tid = otid(), lane = tid & 63, w = tid >> 6, r = lane & 15, q = lane >> 4;
;   constexpr int NT_ = (DK / 16) * NE;
; #pragma unroll
;   for (int ti = 0; ti < (NT_ + 7) / 8; ++ti) {
;     const int tl = w + 8 * ti;
;     if (tl < NT_) {
;       const int dt = tl / NE, et = tl % NE;
;       f32x4 acc = f32x4{0.f, 0.f, 0.f, 0.f};
; #pragma unroll
;       for (int k0 = 0; k0 < 128; k0 += 32) {
;         const bf16x8 a = *(const bf16x8*)(KxT + (16 * dt + r) * 136 + k0 + q * 8);
;         const bf16x8 bv = *(const bf16x8*)(VxT + (16 * et + r) * 136 + k0 + q * 8);
;         acc = MFMA(a, bv, acc);
;       }
;       if (et < 4) {
; #pragma unroll
;         for (int j = 0; j < 4; ++j) outc[(16 * dt + 4 * q + j) * 64 + 16 * et + r] = acc[j];
;       } else if (r == 0) {
; #pragma unroll
;         for (int j = 0; j < 4; ++j) outn[16 * dt + 4 * q + j] = acc[j];
;       }
;     }
;   }
; }
; __device__ __forceinline__ void load_vxT(const bf16* vsrc, bf16* VxT, int c, int rbase, int rpad) {
;   const int tid = otid(), e0 = (tid >> 7) * 16, t = tid & 127;
;   const bf16* vs = vsrc + TROW(t) * US + e0;
;   const uint4 v0 = *(const uint4*)vs, v1 = *(const uint4*)(vs + 8);
;   VxT[(e0 + 0) * 136 + t] = (bf16)(v0.x & 0xffffu); VxT[(e0 + 1) * 136 + t] = (bf16)(v0.x >> 16);
;   VxT[(e0 + 2) * 136 + t] = (bf16)(v0.y & 0xffffu); VxT[(e0 + 3) * 136 + t] = (bf16)(v0.y >> 16);
;   VxT[(e0 + 4) * 136 + t] = (bf16)(v0.z & 0xffffu); VxT[(e0 + 5) * 136 + t] = (bf16)(v0.z >> 16);
; __device__ void gla_prep_unit(const P& p, int layer, int unit, char* smem) {
;     ...
; #pragma unroll
;     for (int i = 0; i < 8; ++i) KxT[(d0 + i) * 136 + t] = f2bf(kx8[i]);
;     uint4 qo, ko;
;     qo.x = pk2(qd[0], qd[1]); qo.y = pk2(qd[2], qd[3]); qo.z = pk2(qd[4], qd[5]); qo.w = pk2(qd[6], qd[7]);
;     ko.x = pk2(kd[0], kd[1]); ko.y = pk2(kd[2], kd[3]); ko.z = pk2(kd[4], kd[5]); ko.w = pk2(kd[6], kd[7]);
;     *(uint4*)qp = qo; *(uint4*)kp = ko;
;     load_vxT(p.U() + C_GV + h * 64, VxT, c, rbase, rpad);
;   }
;   __syncthreads();
;   local_mfma<32, 4>(KxT, VxT, p.gla_loc() + (size_t)unit * 2048, nullptr);
;   if (tid < 32) p.gla_dec()[unit * 32 + tid] = __expf(cl[tid]);
	v_mul_f32_e32 v27, 0x3fb8aa3b, v0
	v_exp_f32_e32 v27, v27
	s_nop 0
	v_mul_f32_e32 v12, v12, v27
	v_mul_f32_e32 v27, 0xbfb8aa3b, v0
	v_sub_f32_e32 v0, v2, v0
	v_mul_f32_e32 v2, 0x3e3504f3, v16
	v_mul_f32_e32 v16, 0x3fb8aa3b, v1
	v_exp_f32_e32 v16, v16
	v_mul_f32_e32 v0, 0x3fb8aa3b, v0
	v_exp_f32_e32 v27, v27
	v_exp_f32_e32 v0, v0
	v_mul_f32_e32 v16, v2, v16
	v_mul_f32_e32 v2, 0xbfb8aa3b, v1
	v_sub_f32_e32 v1, v3, v1
	v_mul_f32_e32 v1, 0x3fb8aa3b, v1
	v_exp_f32_e32 v2, v2
	v_exp_f32_e32 v1, v1
	v_mul_f32_e32 v27, v27, v17
	v_mul_f32_e32 v0, v0, v17
	v_mul_f32_e32 v17, v2, v13
	v_mul_f32_e32 v1, v1, v13
	v_lshlrev_b32_e32 v2, 1, v31
	v_mul_u32_u24_e32 v13, 0x110, v32
	v_cvt_pk_bf16_f32 v3, v14, v139
	v_add3_u32 v2, s45, v2, v13
	ds_write_b16 v2, v3 offset:17024
	v_cvt_pk_bf16_f32 v3, v15, v139
	ds_write_b16 v2, v3 offset:17296
	v_cvt_pk_bf16_f32 v3, v20, v139
	ds_write_b16 v2, v3 offset:17568
	v_cvt_pk_bf16_f32 v3, v21, v139
	ds_write_b16 v2, v3 offset:17840
	v_cvt_pk_bf16_f32 v3, v18, v139
	v_cvt_pk_bf16_f32 v0, v0, v139
	ds_write_b16 v2, v3 offset:18112
	v_cvt_pk_bf16_f32 v3, v19, v139
	ds_write_b16 v2, v0 offset:18656
	v_cvt_pk_bf16_f32 v0, v1, v139
	ds_write_b16 v2, v3 offset:18384
	ds_write_b16 v2, v0 offset:18928
	v_cvt_pk_bf16_f32 v0, v5, v7
	v_cvt_pk_bf16_f32 v1, v22, v24
	v_cvt_pk_bf16_f32 v2, v25, v26
	v_cvt_pk_bf16_f32 v3, v12, v16
	v_cvt_pk_bf16_f32 v5, v23, v28
	v_cvt_pk_bf16_f32 v7, v27, v17
	s_add_u32 s22, s76, 0x6180000
	s_addc_u32 s23, s77, 0
	s_add_u32 s22, s22, s21
	s_addc_u32 s23, s23, 0
	v_and_b32_e32 v230, 0x7f, v136
	v_cmp_gt_u32_e32 vcc, s44, v230
	s_and_b64 vcc, s[14:15], vcc
	v_mov_b32_e32 v224, s19
	v_mov_b32_e32 v225, s20
	v_cndmask_b32_e32 v224, v224, v225, vcc
	v_ashrrev_i32_e32 v231, 3, v136
	v_add_u32_e32 v224, v224, v230
	v_and_b32_e32 v228, -16, v231
	v_mov_b32_e32 v222, s22
	v_mov_b32_e32 v223, s23
	v_mad_i64_i32 v[222:223], s[24:25], v224, s54, v[222:223]
	v_ashrrev_i32_e32 v229, 31, v228
	v_lshl_add_u64 v[226:227], v[228:229], 1, v[222:223]
	global_load_dwordx4 v[232:235], v[226:227], off offset:2064
	global_load_dwordx4 v[236:239], v[226:227], off offset:2048
	global_store_dwordx4 v[10:11], v[0:3], off offset:1536
	global_store_dwordx4 v[8:9], v[4:7], off offset:1792
	s_add_u32 s0, s76, s0
	v_mov_b32_e32 v0, v136
	s_addc_u32 s1, s77, 0
	s_add_u32 s0, s0, s21
	v_and_b32_e32 v10, 0x7f, v0
	v_cmp_gt_u32_e32 vcc, s44, v10
	s_addc_u32 s1, s1, 0
	s_and_b64 vcc, s[14:15], vcc
	v_mov_b32_e32 v1, s19
	v_mov_b32_e32 v2, s20
	v_cndmask_b32_e32 v1, v1, v2, vcc
	v_ashrrev_i32_e32 v11, 3, v0
	v_add_u32_e32 v2, v1, v10
	v_and_b32_e32 v8, -16, v11
	v_mov_b64_e32 v[0:1], s[0:1]
	v_mad_i64_i32 v[0:1], s[0:1], v2, s54, v[0:1]
	v_ashrrev_i32_e32 v9, 31, v8
	v_lshl_add_u64 v[4:5], v[8:9], 1, v[0:1]
	s_nop 0
	s_nop 0
	s_nop 0
	v_mul_lo_u32 v8, v8, s11
	v_lshlrev_b32_e32 v9, 1, v10
	v_add3_u32 v8, s45, v8, v9
	s_waitcnt vmcnt(2)
	ds_write_b16 v8, v236 offset:25728
	ds_write_b16_d16_hi v8, v236 offset:26000
	ds_write_b16 v8, v237 offset:26272
	ds_write_b16_d16_hi v8, v237 offset:26544
	ds_write_b16 v8, v238 offset:26816
	ds_write_b16_d16_hi v8, v238 offset:27088
	ds_write_b16 v8, v239 offset:27360
	ds_write_b16_d16_hi v8, v239 offset:27632
	ds_write_b16 v8, v232 offset:27904
	ds_write_b16_d16_hi v8, v232 offset:28176
	ds_write_b16 v8, v233 offset:28448
	ds_write_b16_d16_hi v8, v233 offset:28720
	ds_write_b16 v8, v234 offset:28992
	ds_write_b16_d16_hi v8, v234 offset:29264
	ds_write_b16 v8, v235 offset:29536
	v_or_b32_e32 v0, 15, v11
	v_mul_lo_u32 v0, v0, s11
	v_add3_u32 v0, s45, v0, v9
	ds_write_b16_d16_hi v0, v235 offset:25728
	v_mov_b32_e32 v0, v136
	s_waitcnt lgkmcnt(0)
	s_barrier
	s_nop 0
	v_ashrrev_i32_e32 v1, 6, v0
	v_cmp_gt_i32_e32 vcc, 8, v1
	s_and_saveexec_b64 s[0:1], vcc
	s_cbranch_execz .LBB0_260
	v_lshrrev_b32_e32 v2, 30, v1
	v_add_u32_e32 v2, v1, v2
	v_ashrrev_i32_e32 v12, 2, v2
	v_mul_i32_i24_e32 v2, 4, v12
	v_bfe_u32 v13, v0, 4, 2
	v_sub_u32_e32 v1, v1, v2
	v_and_b32_e32 v0, 15, v0
	v_lshl_or_b32 v14, v1, 4, v0
	v_lshl_or_b32 v0, v12, 4, v0
	v_lshlrev_b32_e32 v2, 4, v13
	v_mul_lo_u32 v0, v0, s11
	v_mul_lo_u32 v1, v14, s11
	v_add3_u32 v16, s45, v0, v2
	v_add3_u32 v15, s45, v1, v2
	ds_read_b128 v[0:3], v16 offset:17024
	ds_read_b128 v[4:7], v15 offset:25728
	s_waitcnt lgkmcnt(0)
	v_mfma_f32_16x16x32_bf16 v[0:3], v[0:3], v[4:7], 0
	ds_read_b128 v[4:7], v16 offset:17088
	ds_read_b128 v[8:11], v15 offset:25792
	s_add_u32 s2, s76, s2
	s_addc_u32 s3, s77, 0
	s_waitcnt lgkmcnt(0)
	v_mfma_f32_16x16x32_bf16 v[0:3], v[4:7], v[8:11], v[0:3]
	ds_read_b128 v[4:7], v16 offset:17152
	ds_read_b128 v[8:11], v15 offset:25856
	s_lshl_b32 s4, s33, 13
	s_add_u32 s2, s2, s4
	s_waitcnt lgkmcnt(0)
	v_mfma_f32_16x16x32_bf16 v[0:3], v[4:7], v[8:11], v[0:3]
	ds_read_b128 v[4:7], v16 offset:17216
	ds_read_b128 v[8:11], v15 offset:25920
	s_addc_u32 s3, s3, 0
	s_waitcnt lgkmcnt(0)
	v_mfma_f32_16x16x32_bf16 v[0:3], v[4:7], v[8:11], v[0:3]
	v_lshlrev_b32_e32 v4, 10, v12
	v_lshl_or_b32 v4, v13, 8, v4
	v_add_u32_e32 v4, v4, v14
	v_ashrrev_i32_e32 v5, 31, v4
	v_lshl_add_u64 v[6:7], v[4:5], 2, s[2:3]
	s_nop 2
	global_store_dword v[6:7], v0, off
	v_add_u32_e32 v6, 64, v4
	v_ashrrev_i32_e32 v7, 31, v6
	v_lshl_add_u64 v[6:7], v[6:7], 2, s[2:3]
	v_add_u32_e32 v0, 0x80, v4
	global_store_dword v[6:7], v1, off
	v_ashrrev_i32_e32 v1, 31, v0
	v_lshl_add_u64 v[0:1], v[0:1], 2, s[2:3]
	global_store_dword v[0:1], v2, off
	v_add_u32_e32 v0, 0xc0, v4
	v_ashrrev_i32_e32 v1, 31, v0
	v_lshl_add_u64 v[0:1], v[0:1], 2, s[2:3]
	global_store_dword v[0:1], v3, off
